# adds: stick-breaking attention reads its wave-done flags with batched ds_read_b32 instead of 8 serialized flat loads; per-subtile flag read no longer drains the K/V prefetch
# speedup vs baseline: 1.0252x; 1.0008x over previous
; DI float ex2(float x) { return __builtin_amdgcn_exp2f(x); }
; DI float lg2(float x) { return __builtin_amdgcn_logf(x); }
; template <int TYPE>
; DI void attn_item(const Params& p, int layer, int head, int qt, int dil, int res, int chunk, char* smem) {
;     ...
;     __syncthreads();
;     if (TYPE == 2) {
;       if ((sflag[0] & sflag[1] & sflag[2] & sflag[3] & sflag[4] & sflag[5] & sflag[6] & sflag[7]) != 0) break;
;     }
;     *(uint4*)(sK + swz(kkey0, kchunk)) = kreg0;
;     ...
;     ATT_VSTORE(vreg0, vdc0)
;     __syncthreads();
;     ATT_PREFETCH((kt > kt_lo) ? kt - 1 : kt);
;     __builtin_amdgcn_sched_barrier(0);
;     const int Kb = kt * 64;
; #pragma unroll
;     ...
;       const int Ks = Kb + 32 * sub;
;       bool need;
;       if (TYPE == 0) need = (Ks <= wq0 + 31) && (Ks + 31 >= wq0 - 128);
;       else if (TYPE == 1) need = (Ks <= wq0 + 31);
;       else need = (Ks < wq0 + 31) && (sflag[wid] == 0);
;       if (!need) continue;
;       const int db = Uq - Ks - 4 * h;
;     ...
; #pragma unroll
;         for (int i = 0; i < 16; ++i) {
;           const int ci = (i & 3) + 8 * (i >> 2);
;           const float z = s1[i];
;           const float t = lg2(1.f + ex2(-fabsf(z)));
;           float f = -(fmaxf(z, 0.f) + t);
;           float g = fminf(z, 0.f) - t;
;           if (masked) {
;             const bool ok = (db - ci) > 0;
;             f = ok ? f : 0.f;
;             g = ok ? g : -1e30f;
;           }
;           lf[i] = f;
;           lsg[i] = g;
;           tsum += f;
;         }
.LBB0_234:
	v_mov_b32_e32 v105, v101
	s_waitcnt lgkmcnt(0)
	s_barrier
	ds_read_b32 v0, v100
	ds_read_b32 v34, v104
	v_mov_b32_e32 v107, v101
	v_mov_b32_e32 v109, v101
	ds_read_b32 v35, v106
	ds_read_b32 v36, v108
	v_mov_b32_e32 v111, v101
	v_mov_b32_e32 v113, v101
	ds_read_b32 v37, v110
	ds_read_b32 v38, v112
	v_mov_b32_e32 v115, v101
	v_mov_b32_e32 v117, v101
	ds_read_b32 v39, v114
	ds_read_b32 v40, v116
	s_waitcnt vmcnt(0)
	s_or_b64 s[58:59], s[58:59], exec
	s_waitcnt lgkmcnt(0)
	v_and_b32_e32 v0, v34, v0
	v_bitop3_b32 v0, v0, v36, v35 bitop3:0x80
	v_bitop3_b32 v0, v0, v38, v37 bitop3:0x80
	v_bitop3_b32 v0, v0, v40, v39 bitop3:0x80
	v_cmp_eq_u32_e64 s[0:1], 0, v0
	s_and_saveexec_b64 s[60:61], s[0:1]
	s_cbranch_execz .LBB0_233
	v_min_u32_e32 v0, 1, v132
	v_lshlrev_b32_e32 v0, 6, v0
	v_add_u32_e32 v34, v137, v99
	v_sub_u32_e32 v34, v34, v0
	v_add_u32_e32 v35, v136, v99
	v_sub_u32_e32 v0, v35, v0
	v_mad_i64_i32 v[34:35], s[0:1], v34, s67, v[120:121]
	ds_write_b128 v139, v[74:77]
	ds_write_b16 v140, v70 offset:8192
	ds_write_b16_d16_hi v140, v70 offset:8320
	ds_write_b16 v141, v71 offset:8192
	ds_write_b16_d16_hi v142, v71 offset:8192
	ds_write_b16 v143, v72 offset:8192
	ds_write_b16_d16_hi v144, v72 offset:8192
	ds_write_b16 v145, v73 offset:8192
	ds_write_b16_d16_hi v146, v73 offset:8192
	s_waitcnt lgkmcnt(0)
	s_barrier
	v_mad_u64_u32 v[36:37], s[0:1], v0, s67, v[122:123]
	global_load_dwordx4 v[74:77], v[34:35], off
	global_load_dwordx4 v[70:73], v[36:37], off
	v_add_u32_e32 v0, 0x3fe0, v99
	v_cmp_lt_i32_e64 s[0:1], v0, v133
	s_and_saveexec_b64 s[62:63], s[0:1]
	s_cbranch_execz .LBB0_239
	ds_read_b32 v0, v124
	s_waitcnt lgkmcnt(0)
	v_cmp_eq_u32_e64 s[0:1], 0, v0
	s_and_saveexec_b64 s[64:65], s[0:1]
	s_cbranch_execz .LBB0_238
	ds_read_b128 v[34:37], v147 offset:4096
	ds_read_b128 v[82:85], v148 offset:4096
	v_add_u32_e32 v0, 0x3fff, v99
	v_add_u32_e32 v105, 27, v135
	v_add_u32_e32 v107, 26, v135
	s_waitcnt lgkmcnt(1)
	v_mfma_f32_32x32x16_bf16 v[34:49], v[34:37], v[50:53], 0
	v_cmp_lt_i32_e64 s[2:3], v0, v130
	v_cmp_lt_i32_e64 s[0:1], 0, v105
	v_cmp_lt_i32_e64 s[4:5], 0, v107
	v_add_u32_e32 v109, 25, v135
	v_cmp_lt_i32_e64 s[6:7], 0, v109
	s_or_b64 s[0:1], s[2:3], s[0:1]
	s_waitcnt lgkmcnt(0)
	v_mfma_f32_32x32x16_bf16 v[34:49], v[82:85], v[54:57], v[34:49]
	ds_read_b128 v[152:155], v149 offset:4096
	ds_read_b128 v[94:97], v149 offset:8192
	ds_read_b128 v[168:171], v150 offset:4096
	ds_read_b128 v[90:93], v149 offset:12288
	ds_read_b128 v[86:89], v150 offset:8192
	ds_read_b128 v[82:85], v150 offset:12288
	s_waitcnt lgkmcnt(5)
	v_mfma_f32_32x32x16_bf16 v[34:49], v[152:155], v[58:61], v[34:49]
	s_waitcnt lgkmcnt(3)
	v_mfma_f32_32x32x16_bf16 v[34:49], v[168:171], v[62:65], v[34:49]
	s_nop 11
	v_exp_f32_e64 v0, -|v34|
	v_exp_f32_e64 v105, -|v35|
	v_exp_f32_e64 v107, -|v36|
	v_max_f32_e32 v34, v34, v34
	v_add_f32_e32 v0, 1.0, v0
	v_add_f32_e32 v105, 1.0, v105
	v_log_f32_e32 v0, v0
	v_add_f32_e32 v107, 1.0, v107
	v_log_f32_e32 v105, v105
	v_log_f32_e32 v107, v107
	v_exp_f32_e64 v109, -|v37|
	v_max_f32_e32 v35, v35, v35
	v_max_f32_e32 v36, v36, v36
	v_max_f32_e32 v111, 0, v34
	v_min_f32_e32 v34, 0, v34
	v_max_f32_e32 v113, 0, v35
	v_min_f32_e32 v35, 0, v35
	v_max_f32_e32 v115, 0, v36
	v_min_f32_e32 v36, 0, v36
	v_add_f32_e32 v111, v111, v0
	v_sub_f32_e32 v0, v34, v0
	v_add_f32_e32 v34, v113, v105
	v_sub_f32_e32 v35, v35, v105
	v_add_f32_e32 v105, v115, v107
	v_sub_f32_e32 v36, v36, v107
	v_cndmask_b32_e64 v107, 0, -v111, s[0:1]
	v_cndmask_b32_e64 v0, v128, v0, s[0:1]
	s_or_b64 s[0:1], s[2:3], s[4:5]
	v_cndmask_b32_e64 v113, v128, v35, s[0:1]
	v_add_f32_e32 v35, 1.0, v109
	v_log_f32_e32 v35, v35
	v_cndmask_b32_e64 v111, 0, -v34, s[0:1]
	s_or_b64 s[0:1], s[2:3], s[6:7]
	v_cndmask_b32_e64 v115, v128, v36, s[0:1]
	v_max_f32_e32 v36, v37, v37
	v_max_f32_e32 v37, 0, v36
	v_min_f32_e32 v36, 0, v36
	v_add_f32_e32 v37, v37, v35
	v_sub_f32_e32 v35, v36, v35
	v_add_u32_e32 v36, 24, v135
	v_cndmask_b32_e64 v105, 0, -v105, s[0:1]
	v_cmp_lt_i32_e64 s[0:1], 0, v36
	v_exp_f32_e64 v36, -|v38|
	s_or_b64 s[0:1], s[2:3], s[0:1]
	v_cndmask_b32_e64 v109, v128, v35, s[0:1]
	v_cndmask_b32_e64 v37, 0, -v37, s[0:1]
	v_add_f32_e32 v35, 1.0, v36
	v_log_f32_e32 v35, v35
	v_max_f32_e32 v36, v38, v38
	v_max_f32_e32 v38, 0, v36
	v_min_f32_e32 v36, 0, v36
	v_add_f32_e32 v38, v38, v35
	v_sub_f32_e32 v35, v36, v35
	v_add_u32_e32 v36, 19, v135
	v_cmp_lt_i32_e64 s[0:1], 0, v36
	v_exp_f32_e64 v36, -|v39|
	s_or_b64 s[0:1], s[2:3], s[0:1]
	v_cndmask_b32_e64 v117, v128, v35, s[0:1]
	v_cndmask_b32_e64 v38, 0, -v38, s[0:1]
	v_add_f32_e32 v35, 1.0, v36
	v_log_f32_e32 v35, v35
	v_max_f32_e32 v36, v39, v39
	v_max_f32_e32 v39, 0, v36
	v_min_f32_e32 v36, 0, v36
	v_add_f32_e32 v39, v39, v35
	v_sub_f32_e32 v35, v36, v35
	v_add_u32_e32 v36, 18, v135
	v_cmp_lt_i32_e64 s[0:1], 0, v36
	v_exp_f32_e64 v36, -|v40|
	s_or_b64 s[0:1], s[2:3], s[0:1]
	v_cndmask_b32_e64 v151, v128, v35, s[0:1]
	v_cndmask_b32_e64 v39, 0, -v39, s[0:1]
	v_add_f32_e32 v35, 1.0, v36
	v_log_f32_e32 v35, v35
	v_max_f32_e32 v36, v40, v40
	v_max_f32_e32 v40, 0, v36
	v_min_f32_e32 v36, 0, v36
	v_add_f32_e32 v40, v40, v35
	v_sub_f32_e32 v35, v36, v35
	v_add_u32_e32 v36, 17, v135
	v_cmp_lt_i32_e64 s[0:1], 0, v36
	v_exp_f32_e64 v36, -|v41|
	s_or_b64 s[0:1], s[2:3], s[0:1]
	v_cndmask_b32_e64 v156, v128, v35, s[0:1]
	v_cndmask_b32_e64 v40, 0, -v40, s[0:1]
	v_add_f32_e32 v35, 1.0, v36
	v_log_f32_e32 v35, v35
	v_max_f32_e32 v36, v41, v41
	v_max_f32_e32 v41, 0, v36
	v_min_f32_e32 v36, 0, v36
	v_add_f32_e32 v41, v41, v35
	v_sub_f32_e32 v35, v36, v35
	v_add_u32_e32 v36, 16, v135
	v_cmp_lt_i32_e64 s[0:1], 0, v36
	v_exp_f32_e64 v36, -|v42|
; DI float bflo(unsigned u) { return __uint_as_float(u << 16); }
; DI float bfhi(unsigned u) { return __uint_as_float(u & 0xffff0000u); }
; DI f32x16 mfma32(bf16x8 a, bf16x8 b, f32x16 c) { return __builtin_amdgcn_mfma_f32_32x32x16_bf16(a, b, c, 0, 0, 0); }
; DI float ex2(float x) { return __builtin_amdgcn_exp2f(x); }
; DI float lg2(float x) { return __builtin_amdgcn_logf(x); }
; template <int TYPE>
; DI void attn_item(const Params& p, int layer, int head, int qt, int dil, int res, int chunk, char* smem) {
;     ...
; #pragma unroll
;         for (int i = 0; i < 16; ++i) {
;           const int ci = (i & 3) + 8 * (i >> 2);
;           const float z = s1[i];
;           const float t = lg2(1.f + ex2(-fabsf(z)));
;           float f = -(fmaxf(z, 0.f) + t);
;           float g = fminf(z, 0.f) - t;
;           if (masked) {
;             const bool ok = (db - ci) > 0;
;             f = ok ? f : 0.f;
;             g = ok ? g : -1e30f;
;           }
;           lf[i] = f;
;           lsg[i] = g;
;           tsum += f;
;         }
;         unsigned hi[8], lo[8];
; #pragma unroll
;         for (int i = 0; i < 8; ++i) {
;           hi[i] = pack2(lf[2 * i], lf[2 * i + 1]);
;           lo[i] = pack2(lf[2 * i] - bflo(hi[i]), lf[2 * i + 1] - bfhi(hi[i]));
;         }
;         f32x16 aft;
; #pragma unroll
;         for (int i = 0; i < 16; ++i) aft[i] = 0.f;
;         aft = mfma32(Tm0, mk8(hi[0], hi[1], hi[2], hi[3]), aft);
;         aft = mfma32(Tm1, mk8(hi[4], hi[5], hi[6], hi[7]), aft);
;         aft = mfma32(Tm0, mk8(lo[0], lo[1], lo[2], lo[3]), aft);
;         aft = mfma32(Tm1, mk8(lo[4], lo[5], lo[6], lo[7]), aft);
;         float w[16];
; #pragma unroll
;         for (int i = 0; i < 16; ++i) w[i] = ex2(lsg[i] + aft[i] + carry);
;         tsum += __shfl_xor(tsum, 32);
;         carry += tsum;
;         bf16x8 pk0 = mk8(pack2(w[0], w[1]), pack2(w[2], w[3]), pack2(w[4], w[5]), pack2(w[6], w[7]));
;         bf16x8 pk1 = mk8(pack2(w[8], w[9]), pack2(w[10], w[11]), pack2(w[12], w[13]), pack2(w[14], w[15]));
;         O1a = mfma32(vf[0][0], pk0, O1a);
;         O1b = mfma32(vf[0][1], pk0, O1b);
;         O1a = mfma32(vf[1][0], pk1, O1a);
;         O1b = mfma32(vf[1][1], pk1, O1b);
	s_or_b64 s[0:1], s[2:3], s[0:1]
	v_cndmask_b32_e64 v157, v128, v35, s[0:1]
	v_cndmask_b32_e64 v41, 0, -v41, s[0:1]
	v_add_f32_e32 v35, 1.0, v36
	v_log_f32_e32 v35, v35
	v_max_f32_e32 v36, v42, v42
	v_max_f32_e32 v42, 0, v36
	v_min_f32_e32 v36, 0, v36
	v_add_f32_e32 v42, v42, v35
	v_sub_f32_e32 v35, v36, v35
	v_add_u32_e32 v36, 11, v135
	v_cmp_lt_i32_e64 s[0:1], 0, v36
	v_exp_f32_e64 v36, -|v43|
	s_or_b64 s[0:1], s[2:3], s[0:1]
	v_cndmask_b32_e64 v167, v128, v35, s[0:1]
	v_cndmask_b32_e64 v42, 0, -v42, s[0:1]
	v_add_f32_e32 v35, 1.0, v36
	v_log_f32_e32 v35, v35
	v_max_f32_e32 v36, v43, v43
	v_max_f32_e32 v43, 0, v36
	v_min_f32_e32 v36, 0, v36
	v_add_f32_e32 v43, v43, v35
	v_sub_f32_e32 v35, v36, v35
	v_add_u32_e32 v36, 10, v135
	v_cmp_lt_i32_e64 s[0:1], 0, v36
	v_exp_f32_e64 v36, -|v44|
	s_or_b64 s[0:1], s[2:3], s[0:1]
	v_cndmask_b32_e64 v176, v128, v35, s[0:1]
	v_cndmask_b32_e64 v169, 0, -v43, s[0:1]
	v_add_f32_e32 v35, 1.0, v36
	v_log_f32_e32 v35, v35
	v_max_f32_e32 v36, v44, v44
	v_max_f32_e32 v43, 0, v36
	v_min_f32_e32 v36, 0, v36
	v_add_f32_e32 v43, v43, v35
	v_sub_f32_e32 v35, v36, v35
	v_add_u32_e32 v36, 9, v135
	v_cmp_lt_i32_e64 s[0:1], 0, v36
	v_exp_f32_e64 v36, -|v45|
	s_or_b64 s[0:1], s[2:3], s[0:1]
	v_cndmask_b32_e64 v177, v128, v35, s[0:1]
	v_cndmask_b32_e64 v173, 0, -v43, s[0:1]
	v_add_f32_e32 v35, 1.0, v36
	v_log_f32_e32 v35, v35
	v_max_f32_e32 v36, v45, v45
	v_max_f32_e32 v43, 0, v36
	v_min_f32_e32 v36, 0, v36
	v_add_f32_e32 v43, v43, v35
	v_sub_f32_e32 v35, v36, v35
	v_add_u32_e32 v36, 8, v135
	v_cmp_lt_i32_e64 s[0:1], 0, v36
	v_exp_f32_e64 v36, -|v46|
	s_or_b64 s[0:1], s[2:3], s[0:1]
	v_cndmask_b32_e64 v178, v128, v35, s[0:1]
	v_cndmask_b32_e64 v174, 0, -v43, s[0:1]
	v_add_f32_e32 v35, 1.0, v36
	v_log_f32_e32 v35, v35
	v_max_f32_e32 v36, v46, v46
	v_max_f32_e32 v43, 0, v36
	v_min_f32_e32 v36, 0, v36
	v_add_f32_e32 v43, v43, v35
	v_sub_f32_e32 v35, v36, v35
	v_add_u32_e32 v36, 3, v135
	v_cmp_lt_i32_e64 s[0:1], 0, v36
	v_exp_f32_e64 v36, -|v47|
	s_or_b64 s[0:1], s[2:3], s[0:1]
	v_cndmask_b32_e64 v179, v128, v35, s[0:1]
	v_cndmask_b32_e64 v175, 0, -v43, s[0:1]
	v_add_f32_e32 v35, 1.0, v36
	v_log_f32_e32 v35, v35
	v_max_f32_e32 v36, v47, v47
	v_max_f32_e32 v43, 0, v36
	v_min_f32_e32 v36, 0, v36
	v_add_f32_e32 v43, v43, v35
	v_sub_f32_e32 v35, v36, v35
	v_add_u32_e32 v36, 2, v135
	v_cmp_lt_i32_e64 s[0:1], 0, v36
	v_exp_f32_e64 v36, -|v48|
	s_or_b64 s[0:1], s[2:3], s[0:1]
	v_cndmask_b32_e64 v181, v128, v35, s[0:1]
	v_add_f32_e32 v34, 0, v107
	v_add_f32_e32 v35, 1.0, v36
	v_log_f32_e32 v35, v35
	v_add_f32_e32 v34, v111, v34
	v_max_f32_e32 v36, v48, v48
	v_add_f32_e32 v34, v105, v34
	v_cndmask_b32_e64 v180, 0, -v43, s[0:1]
	v_max_f32_e32 v43, 0, v36
	v_min_f32_e32 v36, 0, v36
	v_add_f32_e32 v34, v37, v34
	v_add_f32_e32 v43, v43, v35
	v_sub_f32_e32 v35, v36, v35
	v_add_u32_e32 v36, 1, v135
	v_add_f32_e32 v34, v38, v34
	v_cmp_lt_i32_e64 s[0:1], 0, v36
	v_exp_f32_e64 v36, -|v49|
	v_add_f32_e32 v34, v39, v34
	v_add_f32_e32 v34, v40, v34
	v_add_f32_e32 v34, v41, v34
	s_or_b64 s[0:1], s[2:3], s[0:1]
	v_add_f32_e32 v34, v42, v34
	v_cndmask_b32_e64 v183, v128, v35, s[0:1]
	v_add_f32_e32 v35, 1.0, v36
	v_add_f32_e32 v34, v169, v34
	v_log_f32_e32 v35, v35
	v_add_f32_e32 v34, v173, v34
	v_add_f32_e32 v34, v174, v34
	v_max_f32_e32 v36, v49, v49
	v_add_f32_e32 v34, v175, v34
	v_cndmask_b32_e64 v182, 0, -v43, s[0:1]
	v_max_f32_e32 v43, 0, v36
	v_cmp_lt_i32_e64 s[0:1], 0, v135
	v_add_f32_e32 v34, v180, v34
	v_add_f32_e32 v43, v43, v35
	s_or_b64 s[0:1], s[2:3], s[0:1]
	v_add_f32_e32 v34, v182, v34
	v_min_f32_e32 v36, 0, v36
	v_cndmask_b32_e64 v184, 0, -v43, s[0:1]
	v_sub_f32_e32 v35, v36, v35
	v_add_f32_e32 v186, v184, v34
	v_cvt_pk_bf16_f32 v34, v107, v111
	v_cndmask_b32_e64 v185, v128, v35, s[0:1]
	v_lshlrev_b32_e32 v35, 16, v34
	v_and_b32_e32 v36, 0xffff0000, v34
	v_sub_f32_e32 v35, v107, v35
	v_sub_f32_e32 v36, v111, v36
	v_cvt_pk_bf16_f32 v152, v35, v36
	v_cvt_pk_bf16_f32 v35, v105, v37
	v_lshlrev_b32_e32 v36, 16, v35
	v_and_b32_e32 v43, 0xffff0000, v35
	v_sub_f32_e32 v36, v105, v36
	v_sub_f32_e32 v37, v37, v43
	v_cvt_pk_bf16_f32 v153, v36, v37
	v_cvt_pk_bf16_f32 v36, v38, v39
	v_lshlrev_b32_e32 v37, 16, v36
	v_sub_f32_e32 v37, v38, v37
	v_and_b32_e32 v38, 0xffff0000, v36
	v_sub_f32_e32 v38, v39, v38
	v_cvt_pk_bf16_f32 v154, v37, v38
	v_cvt_pk_bf16_f32 v37, v40, v41
	v_lshlrev_b32_e32 v38, 16, v37
	v_and_b32_e32 v39, 0xffff0000, v37
	v_sub_f32_e32 v38, v40, v38
	v_sub_f32_e32 v39, v41, v39
	v_cvt_pk_bf16_f32 v168, v42, v169
	v_cvt_pk_bf16_f32 v155, v38, v39
	v_lshlrev_b32_e32 v38, 16, v168
	v_sub_f32_e32 v105, v42, v38
	v_mfma_f32_32x32x16_bf16 v[34:49], v[66:69], v[34:37], 0
	v_and_b32_e32 v107, 0xffff0000, v168
	v_sub_f32_e32 v107, v169, v107
	v_cvt_pk_bf16_f32 v169, v173, v174
	v_cvt_pk_bf16_f32 v170, v175, v180
	v_cvt_pk_bf16_f32 v171, v182, v184
	v_cvt_pk_bf16_f32 v172, v105, v107
	v_lshlrev_b32_e32 v105, 16, v169
	v_mfma_f32_32x32x16_bf16 v[34:49], v[78:81], v[168:171], v[34:49]
	v_and_b32_e32 v107, 0xffff0000, v169
	v_sub_f32_e32 v105, v173, v105
	v_sub_f32_e32 v107, v174, v107
	v_cvt_pk_bf16_f32 v173, v105, v107
	v_lshlrev_b32_e32 v105, 16, v170
	v_and_b32_e32 v107, 0xffff0000, v170
	v_sub_f32_e32 v105, v175, v105
	v_mfma_f32_32x32x16_bf16 v[34:49], v[66:69], v[152:155], v[34:49]
	v_sub_f32_e32 v107, v180, v107
	v_cvt_pk_bf16_f32 v174, v105, v107
	v_lshlrev_b32_e32 v105, 16, v171
	v_and_b32_e32 v107, 0xffff0000, v171
	v_sub_f32_e32 v105, v182, v105
	v_sub_f32_e32 v107, v184, v107
	v_cvt_pk_bf16_f32 v175, v105, v107
	v_cmp_lt_i32_e64 s[0:1], v159, v165
	s_nop 0
	v_mfma_f32_32x32x16_bf16 v[34:49], v[78:81], v[172:175], v[34:49]
	s_nop 11
	v_add_f32_e32 v0, v0, v34
	v_add_f32_e32 v34, v113, v35
	v_add_f32_e32 v35, v115, v36
	v_add_f32_e32 v36, v109, v37
	v_add_f32_e32 v37, v117, v38
	v_add_f32_e32 v38, v151, v39
	v_add_f32_e32 v39, v156, v40
	v_add_f32_e32 v40, v157, v41
	v_add_f32_e32 v0, v138, v0
	v_add_f32_e32 v34, v138, v34
	v_add_f32_e32 v35, v138, v35
	v_add_f32_e32 v36, v138, v36
	v_add_f32_e32 v37, v138, v37
	v_add_f32_e32 v38, v138, v38
	v_add_f32_e32 v39, v138, v39
	v_add_f32_e32 v40, v138, v40
	v_exp_f32_e32 v0, v0
	v_exp_f32_e32 v34, v34
	v_exp_f32_e32 v35, v35
	v_exp_f32_e32 v36, v36
	v_exp_f32_e32 v37, v37
	v_exp_f32_e32 v38, v38
	v_exp_f32_e32 v39, v39
	v_exp_f32_e32 v40, v40
	v_cvt_pk_bf16_f32 v34, v0, v34
	v_cvt_pk_bf16_f32 v35, v35, v36
	v_cvt_pk_bf16_f32 v36, v37, v38
	v_cvt_pk_bf16_f32 v37, v39, v40
	v_add_f32_e32 v41, v167, v42
	v_add_f32_e32 v42, v176, v43
	v_mfma_f32_32x32x16_bf16 v[18:33], v[94:97], v[34:37], v[18:33]
	v_add_f32_e32 v43, v177, v44
	v_add_f32_e32 v44, v178, v45
	v_add_f32_e32 v45, v179, v46
	v_add_f32_e32 v46, v181, v47
	v_add_f32_e32 v38, v183, v48
	v_add_f32_e32 v39, v185, v49
	v_add_f32_e32 v41, v138, v41
	s_waitcnt lgkmcnt(2)
; DI f32x16 mfma32(bf16x8 a, bf16x8 b, f32x16 c) { return __builtin_amdgcn_mfma_f32_32x32x16_bf16(a, b, c, 0, 0, 0); }
; DI float ex2(float x) { return __builtin_amdgcn_exp2f(x); }
; template <int TYPE>
; DI void attn_item(const Params& p, int layer, int head, int qt, int dil, int res, int chunk, char* smem) {
;     ...
;         float w[16];
; #pragma unroll
;         for (int i = 0; i < 16; ++i) w[i] = ex2(lsg[i] + aft[i] + carry);
;         tsum += __shfl_xor(tsum, 32);
;         carry += tsum;
;         bf16x8 pk0 = mk8(pack2(w[0], w[1]), pack2(w[2], w[3]), pack2(w[4], w[5]), pack2(w[6], w[7]));
;         bf16x8 pk1 = mk8(pack2(w[8], w[9]), pack2(w[10], w[11]), pack2(w[12], w[13]), pack2(w[14], w[15]));
;         O1a = mfma32(vf[0][0], pk0, O1a);
;         O1b = mfma32(vf[0][1], pk0, O1b);
;         O1a = mfma32(vf[1][0], pk1, O1a);
;         O1b = mfma32(vf[1][1], pk1, O1b);
	v_mfma_f32_32x32x16_bf16 v[2:17], v[90:93], v[34:37], v[2:17]
	v_add_f32_e32 v42, v138, v42
	v_add_f32_e32 v43, v138, v43
	v_add_f32_e32 v44, v138, v44
	v_add_f32_e32 v45, v138, v45
	v_add_f32_e32 v46, v138, v46
	v_add_f32_e32 v38, v138, v38
	v_add_f32_e32 v39, v138, v39
	v_exp_f32_e32 v41, v41
	v_exp_f32_e32 v42, v42
	v_exp_f32_e32 v43, v43
	v_exp_f32_e32 v44, v44
	v_exp_f32_e32 v45, v45
	v_exp_f32_e32 v0, v46
	v_exp_f32_e32 v38, v38
	v_exp_f32_e32 v39, v39
	v_cndmask_b32_e64 v34, v164, v159, s[0:1]
	v_lshlrev_b32_e32 v40, 2, v34
	v_cvt_pk_bf16_f32 v34, v41, v42
	v_cvt_pk_bf16_f32 v35, v43, v44
	v_cvt_pk_bf16_f32 v36, v45, v0
	v_cvt_pk_bf16_f32 v37, v38, v39
	ds_bpermute_b32 v0, v40, v186
	s_waitcnt lgkmcnt(0)
	v_add_f32_e32 v0, v186, v0
	v_mfma_f32_32x32x16_bf16 v[18:33], v[86:89], v[34:37], v[18:33]
	v_add_f32_e32 v138, v138, v0
	v_mfma_f32_32x32x16_bf16 v[2:17], v[82:85], v[34:37], v[2:17]

; DI float ex2(float x) { return __builtin_amdgcn_exp2f(x); }
; template <int TYPE>
; DI void attn_item(const Params& p, int layer, int head, int qt, int dil, int res, int chunk, char* smem) {
;     ...
;       const int Ks = Kb + 32 * sub;
;       bool need;
;       if (TYPE == 0) need = (Ks <= wq0 + 31) && (Ks + 31 >= wq0 - 128);
;       else if (TYPE == 1) need = (Ks <= wq0 + 31);
;       else need = (Ks < wq0 + 31) && (sflag[wid] == 0);
;       if (!need) continue;
;       const int db = Uq - Ks - 4 * h;
;       f32x16 s1, s2;
;       if (TYPE == 2) {
; #pragma unroll
;         for (int i = 0; i < 16; ++i) { s1[i] = 0.f; s2[i] = 0.f; }
;       } else {
;         const float base = -slope * (float)db - cref;
;         const bool msk = (TYPE == 0) ? true : (__builtin_amdgcn_readfirstlane((Ks + 31 > wq0) ? 1 : 0) != 0);
;         if (msk) {
; #pragma unroll
;           for (int i = 0; i < 16; ++i) {
;             const int ci = (i & 3) + 8 * (i >> 2);
;             const int dist = db - ci;
;             s1[i] = (dist >= 0 && dist <= wlim) ? fmaf(slope, (float)ci, base) : -1e30f;
;             s2[i] = s1[i];
;           }
;         } else {
; #pragma unroll
;           for (int i = 0; i < 16; ++i) {
;             const int ci = (i & 3) + 8 * (i >> 2);
;             s1[i] = fmaf(slope, (float)ci, base);
;             s2[i] = s1[i];
;           }
;         }
;       }
;       {
;         bf16x8 kf[4];
; #pragma unroll
;         for (int ks = 0; ks < 4; ++ks) kf[ks] = *(const bf16x8*)(sK + swz(32 * sub + ql, 2 * ks + h));
;         if (TYPE == 1) {
;           s1 = mfma32(kf[0], qf[0], s1);
;           s1 = mfma32(kf[1], qf[1], s1);
;           s2 = mfma32(kf[2], qf[2], s2);
;           s2 = mfma32(kf[3], qf[3], s2);
;         } else {
; #pragma unroll
;           for (int ks = 0; ks < 4; ++ks) s1 = mfma32(kf[ks], qf[ks], s1);
;         }
;     ...
; #pragma unroll
;         for (int i = 0; i < 16; ++i) {
;           const int ci = (i & 3) + 8 * (i >> 2);
;           const float z = s1[i];
;           const float t = lg2(1.f + ex2(-fabsf(z)));
;           float f = -(fmaxf(z, 0.f) + t);
;           float g = fminf(z, 0.f) - t;
;           if (masked) {
;             const bool ok = (db - ci) > 0;
;             f = ok ? f : 0.f;
;             g = ok ? g : -1e30f;
;           }
;           lf[i] = f;
;           lsg[i] = g;
;           tsum += f;
;         }
.LBB0_239:
	s_or_b64 exec, exec, s[62:63]
	v_add_u32_e32 v0, 0x3fc0, v99
	v_cmp_lt_i32_e64 s[0:1], v0, v133
	s_and_saveexec_b64 s[62:63], s[0:1]
	s_cbranch_execz .LBB0_243
	ds_read_b32 v0, v124
	s_waitcnt lgkmcnt(0)
	v_cmp_eq_u32_e64 s[0:1], 0, v0
	s_and_saveexec_b64 s[64:65], s[0:1]
	s_cbranch_execz .LBB0_242
	ds_read_b128 v[34:37], v147
	ds_read_b128 v[94:97], v147 offset:8192
	ds_read_b128 v[82:85], v148
	ds_read_b128 v[90:93], v147 offset:12288
	v_add_u32_e32 v0, 0x3fdf, v99
	v_add_u32_e32 v105, 59, v135
	s_waitcnt lgkmcnt(3)
	v_mfma_f32_32x32x16_bf16 v[34:49], v[34:37], v[50:53], 0
	v_add_u32_e32 v107, 58, v135
	v_cmp_lt_i32_e64 s[2:3], v0, v130
	v_cmp_lt_i32_e64 s[0:1], 0, v105
	v_cmp_lt_i32_e64 s[4:5], 0, v107
	v_add_u32_e32 v109, 57, v135
	v_cmp_lt_i32_e64 s[6:7], 0, v109
	s_or_b64 s[0:1], s[2:3], s[0:1]
	s_waitcnt lgkmcnt(1)
	v_mfma_f32_32x32x16_bf16 v[34:49], v[82:85], v[54:57], v[34:49]
	ds_read_b128 v[152:155], v149
	ds_read_b128 v[168:171], v150
	ds_read_b128 v[86:89], v148 offset:8192
	ds_read_b128 v[82:85], v148 offset:12288
	s_waitcnt lgkmcnt(3)
	v_mfma_f32_32x32x16_bf16 v[34:49], v[152:155], v[58:61], v[34:49]
	s_waitcnt lgkmcnt(2)
	v_mfma_f32_32x32x16_bf16 v[34:49], v[168:171], v[62:65], v[34:49]
	s_nop 11
	v_exp_f32_e64 v0, -|v34|
	v_exp_f32_e64 v105, -|v35|
	v_exp_f32_e64 v107, -|v36|
	v_max_f32_e32 v34, v34, v34
	v_add_f32_e32 v0, 1.0, v0
	v_add_f32_e32 v105, 1.0, v105
	v_log_f32_e32 v0, v0
	v_add_f32_e32 v107, 1.0, v107
	v_log_f32_e32 v105, v105
	v_log_f32_e32 v107, v107
	v_exp_f32_e64 v109, -|v37|
	v_max_f32_e32 v35, v35, v35
	v_max_f32_e32 v36, v36, v36
	v_max_f32_e32 v111, 0, v34
	v_min_f32_e32 v34, 0, v34
	v_max_f32_e32 v113, 0, v35
	v_min_f32_e32 v35, 0, v35
	v_max_f32_e32 v115, 0, v36
	v_min_f32_e32 v36, 0, v36
	v_add_f32_e32 v111, v111, v0
	v_sub_f32_e32 v0, v34, v0
	v_add_f32_e32 v34, v113, v105
	v_sub_f32_e32 v35, v35, v105
	v_add_f32_e32 v105, v115, v107
	v_sub_f32_e32 v36, v36, v107
	v_cndmask_b32_e64 v107, 0, -v111, s[0:1]
	v_cndmask_b32_e64 v0, v128, v0, s[0:1]
	s_or_b64 s[0:1], s[2:3], s[4:5]
	v_cndmask_b32_e64 v113, v128, v35, s[0:1]
	v_add_f32_e32 v35, 1.0, v109
	v_log_f32_e32 v35, v35
	v_cndmask_b32_e64 v111, 0, -v34, s[0:1]
	s_or_b64 s[0:1], s[2:3], s[6:7]
	v_cndmask_b32_e64 v115, v128, v36, s[0:1]
	v_max_f32_e32 v36, v37, v37
	v_max_f32_e32 v37, 0, v36
	v_min_f32_e32 v36, 0, v36
	v_add_f32_e32 v37, v37, v35
	v_sub_f32_e32 v35, v36, v35
	v_add_u32_e32 v36, 56, v135
	v_cndmask_b32_e64 v105, 0, -v105, s[0:1]
	v_cmp_lt_i32_e64 s[0:1], 0, v36
	v_exp_f32_e64 v36, -|v38|
	s_or_b64 s[0:1], s[2:3], s[0:1]
	v_cndmask_b32_e64 v109, v128, v35, s[0:1]
	v_cndmask_b32_e64 v37, 0, -v37, s[0:1]
	v_add_f32_e32 v35, 1.0, v36
	v_log_f32_e32 v35, v35
	v_max_f32_e32 v36, v38, v38
	v_max_f32_e32 v38, 0, v36
	v_min_f32_e32 v36, 0, v36
	v_add_f32_e32 v38, v38, v35
	v_sub_f32_e32 v35, v36, v35
	v_add_u32_e32 v36, 51, v135
	v_cmp_lt_i32_e64 s[0:1], 0, v36
	v_exp_f32_e64 v36, -|v39|
	s_or_b64 s[0:1], s[2:3], s[0:1]
	v_cndmask_b32_e64 v117, v128, v35, s[0:1]
	v_cndmask_b32_e64 v38, 0, -v38, s[0:1]
	v_add_f32_e32 v35, 1.0, v36
	v_log_f32_e32 v35, v35
	v_max_f32_e32 v36, v39, v39
	v_max_f32_e32 v39, 0, v36
	v_min_f32_e32 v36, 0, v36
	v_add_f32_e32 v39, v39, v35
	v_sub_f32_e32 v35, v36, v35
	v_add_u32_e32 v36, 50, v135
	v_cmp_lt_i32_e64 s[0:1], 0, v36
	v_exp_f32_e64 v36, -|v40|
	s_or_b64 s[0:1], s[2:3], s[0:1]
	v_cndmask_b32_e64 v151, v128, v35, s[0:1]
	v_cndmask_b32_e64 v39, 0, -v39, s[0:1]
	v_add_f32_e32 v35, 1.0, v36
	v_log_f32_e32 v35, v35
	v_max_f32_e32 v36, v40, v40
	v_max_f32_e32 v40, 0, v36
	v_min_f32_e32 v36, 0, v36
	v_add_f32_e32 v40, v40, v35
	v_sub_f32_e32 v35, v36, v35
	v_add_u32_e32 v36, 49, v135
	v_cmp_lt_i32_e64 s[0:1], 0, v36
	v_exp_f32_e64 v36, -|v41|
	s_or_b64 s[0:1], s[2:3], s[0:1]
	v_cndmask_b32_e64 v156, v128, v35, s[0:1]
	v_cndmask_b32_e64 v40, 0, -v40, s[0:1]
	v_add_f32_e32 v35, 1.0, v36
	v_log_f32_e32 v35, v35
	v_max_f32_e32 v36, v41, v41
	v_max_f32_e32 v41, 0, v36
	v_min_f32_e32 v36, 0, v36
	v_add_f32_e32 v41, v41, v35
	v_sub_f32_e32 v35, v36, v35
	v_add_u32_e32 v36, 48, v135
	v_cmp_lt_i32_e64 s[0:1], 0, v36
	v_exp_f32_e64 v36, -|v42|
	s_or_b64 s[0:1], s[2:3], s[0:1]
	v_cndmask_b32_e64 v157, v128, v35, s[0:1]
	v_cndmask_b32_e64 v41, 0, -v41, s[0:1]
	v_add_f32_e32 v35, 1.0, v36
	v_log_f32_e32 v35, v35
	v_max_f32_e32 v36, v42, v42
	v_max_f32_e32 v42, 0, v36
	v_min_f32_e32 v36, 0, v36
	v_add_f32_e32 v42, v42, v35
	v_sub_f32_e32 v35, v36, v35
	v_add_u32_e32 v36, 43, v135
	v_cmp_lt_i32_e64 s[0:1], 0, v36
	v_exp_f32_e64 v36, -|v43|
	s_or_b64 s[0:1], s[2:3], s[0:1]
	v_cndmask_b32_e64 v167, v128, v35, s[0:1]
	v_cndmask_b32_e64 v42, 0, -v42, s[0:1]
	v_add_f32_e32 v35, 1.0, v36
	v_log_f32_e32 v35, v35
	v_max_f32_e32 v36, v43, v43
	v_max_f32_e32 v43, 0, v36
	v_min_f32_e32 v36, 0, v36
	v_add_f32_e32 v43, v43, v35
	v_sub_f32_e32 v35, v36, v35
	v_add_u32_e32 v36, 42, v135
	v_cmp_lt_i32_e64 s[0:1], 0, v36
	v_exp_f32_e64 v36, -|v44|
	s_or_b64 s[0:1], s[2:3], s[0:1]
	v_cndmask_b32_e64 v176, v128, v35, s[0:1]
	v_cndmask_b32_e64 v169, 0, -v43, s[0:1]
	v_add_f32_e32 v35, 1.0, v36
	v_log_f32_e32 v35, v35
	v_max_f32_e32 v36, v44, v44
	v_max_f32_e32 v43, 0, v36
	v_min_f32_e32 v36, 0, v36
	v_add_f32_e32 v43, v43, v35
	v_sub_f32_e32 v35, v36, v35
	v_add_u32_e32 v36, 41, v135
	v_cmp_lt_i32_e64 s[0:1], 0, v36
	v_exp_f32_e64 v36, -|v45|
	s_or_b64 s[0:1], s[2:3], s[0:1]
	v_cndmask_b32_e64 v177, v128, v35, s[0:1]
	v_cndmask_b32_e64 v173, 0, -v43, s[0:1]
	v_add_f32_e32 v35, 1.0, v36
	v_log_f32_e32 v35, v35
	v_max_f32_e32 v36, v45, v45
	v_max_f32_e32 v43, 0, v36
	v_min_f32_e32 v36, 0, v36
	v_add_f32_e32 v43, v43, v35
; DI float bflo(unsigned u) { return __uint_as_float(u << 16); }
; DI float bfhi(unsigned u) { return __uint_as_float(u & 0xffff0000u); }
; DI f32x16 mfma32(bf16x8 a, bf16x8 b, f32x16 c) { return __builtin_amdgcn_mfma_f32_32x32x16_bf16(a, b, c, 0, 0, 0); }
; DI float ex2(float x) { return __builtin_amdgcn_exp2f(x); }
; DI float lg2(float x) { return __builtin_amdgcn_logf(x); }
; template <int TYPE>
; DI void attn_item(const Params& p, int layer, int head, int qt, int dil, int res, int chunk, char* smem) {
;     ...
; #pragma unroll
;         for (int i = 0; i < 16; ++i) {
;           const int ci = (i & 3) + 8 * (i >> 2);
;           const float z = s1[i];
;           const float t = lg2(1.f + ex2(-fabsf(z)));
;           float f = -(fmaxf(z, 0.f) + t);
;           float g = fminf(z, 0.f) - t;
;           if (masked) {
;             const bool ok = (db - ci) > 0;
;             f = ok ? f : 0.f;
;             g = ok ? g : -1e30f;
;           }
;           lf[i] = f;
;           lsg[i] = g;
;           tsum += f;
;         }
;         unsigned hi[8], lo[8];
; #pragma unroll
;         for (int i = 0; i < 8; ++i) {
;           hi[i] = pack2(lf[2 * i], lf[2 * i + 1]);
;           lo[i] = pack2(lf[2 * i] - bflo(hi[i]), lf[2 * i + 1] - bfhi(hi[i]));
;         }
;         f32x16 aft;
; #pragma unroll
;         for (int i = 0; i < 16; ++i) aft[i] = 0.f;
;         aft = mfma32(Tm0, mk8(hi[0], hi[1], hi[2], hi[3]), aft);
;         aft = mfma32(Tm1, mk8(hi[4], hi[5], hi[6], hi[7]), aft);
;         aft = mfma32(Tm0, mk8(lo[0], lo[1], lo[2], lo[3]), aft);
;         aft = mfma32(Tm1, mk8(lo[4], lo[5], lo[6], lo[7]), aft);
;         float w[16];
; #pragma unroll
;         for (int i = 0; i < 16; ++i) w[i] = ex2(lsg[i] + aft[i] + carry);
;         tsum += __shfl_xor(tsum, 32);
;         carry += tsum;
;         bf16x8 pk0 = mk8(pack2(w[0], w[1]), pack2(w[2], w[3]), pack2(w[4], w[5]), pack2(w[6], w[7]));
;         bf16x8 pk1 = mk8(pack2(w[8], w[9]), pack2(w[10], w[11]), pack2(w[12], w[13]), pack2(w[14], w[15]));
;         O1a = mfma32(vf[0][0], pk0, O1a);
;         O1b = mfma32(vf[0][1], pk0, O1b);
;         O1a = mfma32(vf[1][0], pk1, O1a);
;         O1b = mfma32(vf[1][1], pk1, O1b);
	v_sub_f32_e32 v35, v36, v35
	v_add_u32_e32 v36, 40, v135
	v_cmp_lt_i32_e64 s[0:1], 0, v36
	v_exp_f32_e64 v36, -|v46|
	s_or_b64 s[0:1], s[2:3], s[0:1]
	v_cndmask_b32_e64 v178, v128, v35, s[0:1]
	v_cndmask_b32_e64 v174, 0, -v43, s[0:1]
	v_add_f32_e32 v35, 1.0, v36
	v_log_f32_e32 v35, v35
	v_max_f32_e32 v36, v46, v46
	v_max_f32_e32 v43, 0, v36
	v_min_f32_e32 v36, 0, v36
	v_add_f32_e32 v43, v43, v35
	v_sub_f32_e32 v35, v36, v35
	v_add_u32_e32 v36, 35, v135
	v_cmp_lt_i32_e64 s[0:1], 0, v36
	v_exp_f32_e64 v36, -|v47|
	s_or_b64 s[0:1], s[2:3], s[0:1]
	v_cndmask_b32_e64 v179, v128, v35, s[0:1]
	v_cndmask_b32_e64 v175, 0, -v43, s[0:1]
	v_add_f32_e32 v35, 1.0, v36
	v_log_f32_e32 v35, v35
	v_max_f32_e32 v36, v47, v47
	v_max_f32_e32 v43, 0, v36
	v_min_f32_e32 v36, 0, v36
	v_add_f32_e32 v43, v43, v35
	v_sub_f32_e32 v35, v36, v35
	v_add_u32_e32 v36, 34, v135
	v_cmp_lt_i32_e64 s[0:1], 0, v36
	v_exp_f32_e64 v36, -|v48|
	s_or_b64 s[0:1], s[2:3], s[0:1]
	v_cndmask_b32_e64 v181, v128, v35, s[0:1]
	v_add_f32_e32 v34, 0, v107
	v_add_f32_e32 v35, 1.0, v36
	v_log_f32_e32 v35, v35
	v_max_f32_e32 v36, v48, v48
	v_cndmask_b32_e64 v180, 0, -v43, s[0:1]
	v_max_f32_e32 v43, 0, v36
	v_min_f32_e32 v36, 0, v36
	v_add_f32_e32 v34, v111, v34
	v_add_f32_e32 v43, v43, v35
	v_sub_f32_e32 v35, v36, v35
	v_add_u32_e32 v36, 33, v135
	v_add_f32_e32 v34, v105, v34
	v_cmp_lt_i32_e64 s[0:1], 0, v36
	v_exp_f32_e64 v36, -|v49|
	v_add_f32_e32 v34, v37, v34
	v_add_f32_e32 v34, v38, v34
	v_add_f32_e32 v34, v39, v34
	s_or_b64 s[0:1], s[2:3], s[0:1]
	v_add_f32_e32 v34, v40, v34
	v_cndmask_b32_e64 v183, v128, v35, s[0:1]
	v_add_f32_e32 v35, 1.0, v36
	v_add_f32_e32 v34, v41, v34
	v_log_f32_e32 v35, v35
	v_add_f32_e32 v34, v42, v34
	v_add_f32_e32 v34, v169, v34
	v_max_f32_e32 v36, v49, v49
	v_add_f32_e32 v34, v173, v34
	v_cndmask_b32_e64 v182, 0, -v43, s[0:1]
	v_max_f32_e32 v43, 0, v36
	v_min_f32_e32 v36, 0, v36
	v_add_f32_e32 v34, v174, v34
	v_add_f32_e32 v43, v43, v35
	v_sub_f32_e32 v35, v36, v35
	v_add_u32_e32 v36, 32, v135
	v_add_f32_e32 v34, v175, v34
	v_cmp_lt_i32_e64 s[0:1], 0, v36
	v_add_f32_e32 v34, v180, v34
	s_or_b64 s[0:1], s[2:3], s[0:1]
	v_add_f32_e32 v34, v182, v34
	v_cndmask_b32_e64 v184, 0, -v43, s[0:1]
	v_add_f32_e32 v186, v184, v34
	v_cvt_pk_bf16_f32 v34, v107, v111
	v_cndmask_b32_e64 v185, v128, v35, s[0:1]
	v_lshlrev_b32_e32 v35, 16, v34
	v_and_b32_e32 v36, 0xffff0000, v34
	v_sub_f32_e32 v35, v107, v35
	v_sub_f32_e32 v36, v111, v36
	v_cvt_pk_bf16_f32 v152, v35, v36
	v_cvt_pk_bf16_f32 v35, v105, v37
	v_lshlrev_b32_e32 v36, 16, v35
	v_and_b32_e32 v43, 0xffff0000, v35
	v_sub_f32_e32 v36, v105, v36
	v_sub_f32_e32 v37, v37, v43
	v_cvt_pk_bf16_f32 v153, v36, v37
	v_cvt_pk_bf16_f32 v36, v38, v39
	v_lshlrev_b32_e32 v37, 16, v36
	v_sub_f32_e32 v37, v38, v37
	v_and_b32_e32 v38, 0xffff0000, v36
	v_sub_f32_e32 v38, v39, v38
	v_cvt_pk_bf16_f32 v154, v37, v38
	v_cvt_pk_bf16_f32 v37, v40, v41
	v_lshlrev_b32_e32 v38, 16, v37
	v_and_b32_e32 v39, 0xffff0000, v37
	v_sub_f32_e32 v38, v40, v38
	v_sub_f32_e32 v39, v41, v39
	v_cvt_pk_bf16_f32 v168, v42, v169
	v_cvt_pk_bf16_f32 v155, v38, v39
	v_lshlrev_b32_e32 v38, 16, v168
	v_sub_f32_e32 v105, v42, v38
	v_mfma_f32_32x32x16_bf16 v[34:49], v[66:69], v[34:37], 0
	v_and_b32_e32 v107, 0xffff0000, v168
	v_sub_f32_e32 v107, v169, v107
	v_cvt_pk_bf16_f32 v169, v173, v174
	v_cvt_pk_bf16_f32 v170, v175, v180
	v_cvt_pk_bf16_f32 v171, v182, v184
	v_cvt_pk_bf16_f32 v172, v105, v107
	v_lshlrev_b32_e32 v105, 16, v169
	v_mfma_f32_32x32x16_bf16 v[34:49], v[78:81], v[168:171], v[34:49]
	v_and_b32_e32 v107, 0xffff0000, v169
	v_sub_f32_e32 v105, v173, v105
	v_sub_f32_e32 v107, v174, v107
	v_cvt_pk_bf16_f32 v173, v105, v107
	v_lshlrev_b32_e32 v105, 16, v170
	v_and_b32_e32 v107, 0xffff0000, v170
	v_sub_f32_e32 v105, v175, v105
	v_mfma_f32_32x32x16_bf16 v[34:49], v[66:69], v[152:155], v[34:49]
	v_sub_f32_e32 v107, v180, v107
	v_cvt_pk_bf16_f32 v174, v105, v107
	v_lshlrev_b32_e32 v105, 16, v171
	v_and_b32_e32 v107, 0xffff0000, v171
	v_sub_f32_e32 v105, v182, v105
	v_sub_f32_e32 v107, v184, v107
	v_cvt_pk_bf16_f32 v175, v105, v107
	v_cmp_lt_i32_e64 s[0:1], v159, v165
	s_nop 0
	v_mfma_f32_32x32x16_bf16 v[34:49], v[78:81], v[172:175], v[34:49]
	s_nop 11
	v_add_f32_e32 v0, v0, v34
	v_add_f32_e32 v34, v113, v35
	v_add_f32_e32 v35, v115, v36
	v_add_f32_e32 v36, v109, v37
	v_add_f32_e32 v37, v117, v38
	v_add_f32_e32 v38, v151, v39
	v_add_f32_e32 v39, v156, v40
	v_add_f32_e32 v40, v157, v41
	v_add_f32_e32 v0, v138, v0
	v_add_f32_e32 v34, v138, v34
	v_add_f32_e32 v35, v138, v35
	v_add_f32_e32 v36, v138, v36
	v_add_f32_e32 v37, v138, v37
	v_add_f32_e32 v38, v138, v38
	v_add_f32_e32 v39, v138, v39
	v_add_f32_e32 v40, v138, v40
	v_exp_f32_e32 v0, v0
	v_exp_f32_e32 v34, v34
	v_exp_f32_e32 v35, v35
	v_exp_f32_e32 v36, v36
	v_exp_f32_e32 v37, v37
	v_exp_f32_e32 v38, v38
	v_exp_f32_e32 v39, v39
	v_exp_f32_e32 v40, v40
	v_cvt_pk_bf16_f32 v34, v0, v34
	v_cvt_pk_bf16_f32 v35, v35, v36
	v_cvt_pk_bf16_f32 v36, v37, v38
	v_cvt_pk_bf16_f32 v37, v39, v40
	v_add_f32_e32 v41, v167, v42
	v_add_f32_e32 v42, v176, v43
	v_mfma_f32_32x32x16_bf16 v[18:33], v[94:97], v[34:37], v[18:33]
	v_add_f32_e32 v43, v177, v44
	v_add_f32_e32 v44, v178, v45
	v_add_f32_e32 v45, v179, v46
	v_add_f32_e32 v46, v181, v47
	v_add_f32_e32 v38, v183, v48
	v_add_f32_e32 v39, v185, v49
	v_add_f32_e32 v41, v138, v41
	v_mfma_f32_32x32x16_bf16 v[2:17], v[90:93], v[34:37], v[2:17]
	v_add_f32_e32 v42, v138, v42
	v_add_f32_e32 v43, v138, v43
	v_add_f32_e32 v44, v138, v44
	v_add_f32_e32 v45, v138, v45
	v_add_f32_e32 v46, v138, v46
	v_add_f32_e32 v38, v138, v38
	v_add_f32_e32 v39, v138, v39
	v_exp_f32_e32 v41, v41
	v_exp_f32_e32 v42, v42
	v_exp_f32_e32 v43, v43
	v_exp_f32_e32 v44, v44
	v_exp_f32_e32 v45, v45
	v_exp_f32_e32 v0, v46
	v_exp_f32_e32 v38, v38
	v_exp_f32_e32 v39, v39
	v_cndmask_b32_e64 v34, v164, v159, s[0:1]
	v_lshlrev_b32_e32 v40, 2, v34
	v_cvt_pk_bf16_f32 v34, v41, v42
	v_cvt_pk_bf16_f32 v35, v43, v44
	v_cvt_pk_bf16_f32 v36, v45, v0
	v_cvt_pk_bf16_f32 v37, v38, v39
	ds_bpermute_b32 v0, v40, v186
	s_waitcnt lgkmcnt(0)
	v_add_f32_e32 v0, v186, v0
	v_mfma_f32_32x32x16_bf16 v[18:33], v[86:89], v[34:37], v[18:33]
	v_add_f32_e32 v138, v138, v0
	v_mfma_f32_32x32x16_bf16 v[2:17], v[82:85], v[34:37], v[2:17]

; template <int TYPE>
; DI void attn_item(const Params& p, int layer, int head, int qt, int dil, int res, int chunk, char* smem) {
;     ...
;     __syncthreads();
;     if (TYPE == 2) {
;       if ((sflag[0] & sflag[1] & sflag[2] & sflag[3] & sflag[4] & sflag[5] & sflag[6] & sflag[7]) != 0) break;
;     }
;     *(uint4*)(sK + swz(kkey0, kchunk)) = kreg0;
;     ...
;     ATT_VSTORE(vreg0, vdc0)
;     __syncthreads();
;     ATT_PREFETCH((kt > kt_lo) ? kt - 1 : kt);
;     __builtin_amdgcn_sched_barrier(0);
;     const int Kb = kt * 64;
; #pragma unroll
;     ...
;       const int Ks = Kb + 32 * sub;
;       bool need;
;       if (TYPE == 0) need = (Ks <= wq0 + 31) && (Ks + 31 >= wq0 - 128);
;       else if (TYPE == 1) need = (Ks <= wq0 + 31);
;       else need = (Ks < wq0 + 31) && (sflag[wid] == 0);
;       if (!need) continue;
;     ...
;       {
;         bf16x8 kf[4];
; #pragma unroll
;         for (int ks = 0; ks < 4; ++ks) kf[ks] = *(const bf16x8*)(sK + swz(32 * sub + ql, 2 * ks + h));
;         if (TYPE == 1) {
;           s1 = mfma32(kf[0], qf[0], s1);
;           s1 = mfma32(kf[1], qf[1], s1);
;           s2 = mfma32(kf[2], qf[2], s2);
;           s2 = mfma32(kf[3], qf[3], s2);
;         } else {
; #pragma unroll
;           for (int ks = 0; ks < 4; ++ks) s1 = mfma32(kf[ks], qf[ks], s1);
;         }
;       }
;       bf16x8 vf[2][2];
; #pragma unroll
;       for (int s = 0; s < 2; ++s)
; #pragma unroll
;         for (int dt = 0; dt < 2; ++dt) vf[s][dt] = *(const bf16x8*)(sV + swz(32 * dt + ql, 4 * sub + 2 * s + h));
;       if (TYPE == 0 || TYPE == 1) {
;         const bool masked = (TYPE == 0) ? true : (Ks + 31 > wq0);
;         bf16x8 pk0, pk1;
;         fx_step(s1, l1, db, masked, wlim, pk0, pk1);
;         O1a = mfma32(vf[0][0], pk0, O1a);
;         O1b = mfma32(vf[0][1], pk0, O1b);
;         O1a = mfma32(vf[1][0], pk1, O1a);
;         O1b = mfma32(vf[1][1], pk1, O1b);
;         if (TYPE == 1) {
;           fx_step(s2, l2, db, masked, wlim, pk0, pk1);
;           O2a = mfma32(vf[0][0], pk0, O2a);
;           O2b = mfma32(vf[0][1], pk0, O2b);
;           O2a = mfma32(vf[1][0], pk1, O2a);
;           O2b = mfma32(vf[1][1], pk1, O2b);
;         }
;       } else {
;         const bool masked = (Ks + 31 >= wq0);
;         float lf[16], lsg[16];
;         float tsum = 0.f;
; #pragma unroll
;         for (int i = 0; i < 16; ++i) {
;           const int ci = (i & 3) + 8 * (i >> 2);
.LBB0_610:
	v_mov_b32_e32 v105, v101
	s_waitcnt lgkmcnt(0)
	s_barrier
	ds_read_b32 v0, v100
	ds_read_b32 v34, v104
	v_mov_b32_e32 v107, v101
	v_mov_b32_e32 v109, v101
	ds_read_b32 v35, v106
	ds_read_b32 v36, v108
	v_mov_b32_e32 v111, v101
	v_mov_b32_e32 v113, v101
	ds_read_b32 v37, v110
	ds_read_b32 v38, v112
	v_mov_b32_e32 v115, v101
	v_mov_b32_e32 v117, v101
	ds_read_b32 v39, v114
	ds_read_b32 v40, v116
	s_waitcnt vmcnt(0)
	s_or_b64 s[48:49], s[48:49], exec
	s_waitcnt lgkmcnt(0)
	v_and_b32_e32 v0, v34, v0
	v_bitop3_b32 v0, v0, v36, v35 bitop3:0x80
	v_bitop3_b32 v0, v0, v38, v37 bitop3:0x80
	v_bitop3_b32 v0, v0, v40, v39 bitop3:0x80
	v_cmp_eq_u32_e64 s[0:1], 0, v0
	s_and_saveexec_b64 s[52:53], s[0:1]
	s_cbranch_execz .LBB0_609
	v_min_u32_e32 v0, 1, v132
	v_lshlrev_b32_e32 v0, 6, v0
	v_add_u32_e32 v34, v137, v99
	v_sub_u32_e32 v34, v34, v0
	v_add_u32_e32 v35, v136, v99
	v_sub_u32_e32 v0, v35, v0
	v_mad_i64_i32 v[34:35], s[0:1], v34, s60, v[120:121]
	ds_write_b128 v139, v[74:77]
	ds_write_b16 v140, v70 offset:8192
	ds_write_b16_d16_hi v140, v70 offset:8320
	ds_write_b16 v141, v71 offset:8192
	ds_write_b16_d16_hi v142, v71 offset:8192
	ds_write_b16 v143, v72 offset:8192
	ds_write_b16_d16_hi v144, v72 offset:8192
	ds_write_b16 v145, v73 offset:8192
	ds_write_b16_d16_hi v146, v73 offset:8192
	s_waitcnt lgkmcnt(0)
	s_barrier
	v_mad_u64_u32 v[36:37], s[0:1], v0, s60, v[122:123]
	global_load_dwordx4 v[74:77], v[34:35], off
	global_load_dwordx4 v[70:73], v[36:37], off
	v_add_u32_e32 v0, 0x3fe0, v99
	v_cmp_lt_i32_e64 s[0:1], v0, v133
	s_and_saveexec_b64 s[54:55], s[0:1]
	s_cbranch_execz .LBB0_615
	ds_read_b32 v0, v124
	s_waitcnt lgkmcnt(0)
	v_cmp_eq_u32_e64 s[0:1], 0, v0
	s_and_saveexec_b64 s[56:57], s[0:1]
	s_cbranch_execz .LBB0_614
	ds_read_b128 v[34:37], v147 offset:4096
	ds_read_b128 v[82:85], v148 offset:4096
	v_add_u32_e32 v0, 0x3fff, v99
	v_add_u32_e32 v105, 27, v135
	v_add_u32_e32 v107, 26, v135
	s_waitcnt lgkmcnt(1)
	v_mfma_f32_32x32x16_bf16 v[34:49], v[34:37], v[50:53], 0
	v_cmp_lt_i32_e64 s[2:3], v0, v130
	v_cmp_lt_i32_e64 s[0:1], 0, v105
	v_cmp_lt_i32_e64 s[4:5], 0, v107
	v_add_u32_e32 v109, 25, v135
	v_cmp_lt_i32_e64 s[6:7], 0, v109
	s_or_b64 s[0:1], s[2:3], s[0:1]
	s_waitcnt lgkmcnt(0)
	v_mfma_f32_32x32x16_bf16 v[34:49], v[82:85], v[54:57], v[34:49]
	ds_read_b128 v[152:155], v149 offset:4096
	ds_read_b128 v[94:97], v149 offset:8192
	ds_read_b128 v[166:169], v150 offset:4096
	ds_read_b128 v[90:93], v149 offset:12288
	ds_read_b128 v[86:89], v150 offset:8192
	ds_read_b128 v[82:85], v150 offset:12288
	s_waitcnt lgkmcnt(5)
	v_mfma_f32_32x32x16_bf16 v[34:49], v[152:155], v[58:61], v[34:49]
	s_waitcnt lgkmcnt(3)
	v_mfma_f32_32x32x16_bf16 v[34:49], v[166:169], v[62:65], v[34:49]
	s_nop 11
	v_exp_f32_e64 v0, -|v34|
	v_exp_f32_e64 v105, -|v35|
	v_exp_f32_e64 v107, -|v36|
	v_max_f32_e32 v34, v34, v34
	v_add_f32_e32 v0, 1.0, v0
	v_add_f32_e32 v105, 1.0, v105
	v_log_f32_e32 v0, v0
	v_add_f32_e32 v107, 1.0, v107
	v_log_f32_e32 v105, v105
	v_log_f32_e32 v107, v107
	v_exp_f32_e64 v109, -|v37|
	v_max_f32_e32 v35, v35, v35
	v_max_f32_e32 v36, v36, v36
	v_max_f32_e32 v111, 0, v34
	v_min_f32_e32 v34, 0, v34
	v_max_f32_e32 v113, 0, v35
	v_min_f32_e32 v35, 0, v35
	v_max_f32_e32 v115, 0, v36
	v_min_f32_e32 v36, 0, v36
	v_add_f32_e32 v111, v111, v0
	v_sub_f32_e32 v0, v34, v0
	v_add_f32_e32 v34, v113, v105
	v_sub_f32_e32 v35, v35, v105
	v_add_f32_e32 v105, v115, v107
	v_sub_f32_e32 v36, v36, v107
	v_cndmask_b32_e64 v107, 0, -v111, s[0:1]
	v_cndmask_b32_e64 v0, v128, v0, s[0:1]
	s_or_b64 s[0:1], s[2:3], s[4:5]
	v_cndmask_b32_e64 v113, v128, v35, s[0:1]
	v_add_f32_e32 v35, 1.0, v109
	v_log_f32_e32 v35, v35
	v_cndmask_b32_e64 v111, 0, -v34, s[0:1]
	s_or_b64 s[0:1], s[2:3], s[6:7]
	v_cndmask_b32_e64 v115, v128, v36, s[0:1]
	v_max_f32_e32 v36, v37, v37
	v_max_f32_e32 v37, 0, v36
	v_min_f32_e32 v36, 0, v36
	v_add_f32_e32 v37, v37, v35
	v_sub_f32_e32 v35, v36, v35
	v_add_u32_e32 v36, 24, v135
	v_cndmask_b32_e64 v105, 0, -v105, s[0:1]
	v_cmp_lt_i32_e64 s[0:1], 0, v36
	v_exp_f32_e64 v36, -|v38|
	s_or_b64 s[0:1], s[2:3], s[0:1]
	v_cndmask_b32_e64 v109, v128, v35, s[0:1]
	v_cndmask_b32_e64 v37, 0, -v37, s[0:1]
	v_add_f32_e32 v35, 1.0, v36
	v_log_f32_e32 v35, v35
	v_max_f32_e32 v36, v38, v38
	v_max_f32_e32 v38, 0, v36
	v_min_f32_e32 v36, 0, v36
	v_add_f32_e32 v38, v38, v35
	v_sub_f32_e32 v35, v36, v35
	v_add_u32_e32 v36, 19, v135
	v_cmp_lt_i32_e64 s[0:1], 0, v36
	v_exp_f32_e64 v36, -|v39|
	s_or_b64 s[0:1], s[2:3], s[0:1]
	v_cndmask_b32_e64 v117, v128, v35, s[0:1]
	v_cndmask_b32_e64 v38, 0, -v38, s[0:1]
	v_add_f32_e32 v35, 1.0, v36
	v_log_f32_e32 v35, v35
	v_max_f32_e32 v36, v39, v39
	v_max_f32_e32 v39, 0, v36
	v_min_f32_e32 v36, 0, v36
	v_add_f32_e32 v39, v39, v35
	v_sub_f32_e32 v35, v36, v35
	v_add_u32_e32 v36, 18, v135
	v_cmp_lt_i32_e64 s[0:1], 0, v36
	v_exp_f32_e64 v36, -|v40|
	s_or_b64 s[0:1], s[2:3], s[0:1]
	v_cndmask_b32_e64 v151, v128, v35, s[0:1]
	v_cndmask_b32_e64 v39, 0, -v39, s[0:1]
	v_add_f32_e32 v35, 1.0, v36
	v_log_f32_e32 v35, v35
	v_max_f32_e32 v36, v40, v40
	v_max_f32_e32 v40, 0, v36
	v_min_f32_e32 v36, 0, v36
	v_add_f32_e32 v40, v40, v35
	v_sub_f32_e32 v35, v36, v35
	v_add_u32_e32 v36, 17, v135
	v_cmp_lt_i32_e64 s[0:1], 0, v36
	v_exp_f32_e64 v36, -|v41|
	s_or_b64 s[0:1], s[2:3], s[0:1]
	v_cndmask_b32_e64 v156, v128, v35, s[0:1]
	v_cndmask_b32_e64 v40, 0, -v40, s[0:1]
	v_add_f32_e32 v35, 1.0, v36
	v_log_f32_e32 v35, v35
	v_max_f32_e32 v36, v41, v41
	v_max_f32_e32 v41, 0, v36
	v_min_f32_e32 v36, 0, v36
	v_add_f32_e32 v41, v41, v35
	v_sub_f32_e32 v35, v36, v35
	v_add_u32_e32 v36, 16, v135
	v_cmp_lt_i32_e64 s[0:1], 0, v36
	v_exp_f32_e64 v36, -|v42|
; DI float bflo(unsigned u) { return __uint_as_float(u << 16); }
; DI float bfhi(unsigned u) { return __uint_as_float(u & 0xffff0000u); }
; DI f32x16 mfma32(bf16x8 a, bf16x8 b, f32x16 c) { return __builtin_amdgcn_mfma_f32_32x32x16_bf16(a, b, c, 0, 0, 0); }
; DI float ex2(float x) { return __builtin_amdgcn_exp2f(x); }
; DI float lg2(float x) { return __builtin_amdgcn_logf(x); }
; template <int TYPE>
; DI void attn_item(const Params& p, int layer, int head, int qt, int dil, int res, int chunk, char* smem) {
;     ...
;         const bool masked = (Ks + 31 >= wq0);
;         float lf[16], lsg[16];
;         float tsum = 0.f;
; #pragma unroll
;         for (int i = 0; i < 16; ++i) {
;           const int ci = (i & 3) + 8 * (i >> 2);
;           const float z = s1[i];
;           const float t = lg2(1.f + ex2(-fabsf(z)));
;           float f = -(fmaxf(z, 0.f) + t);
;           float g = fminf(z, 0.f) - t;
;           if (masked) {
;             const bool ok = (db - ci) > 0;
;             f = ok ? f : 0.f;
;             g = ok ? g : -1e30f;
;           }
;           lf[i] = f;
;           lsg[i] = g;
;           tsum += f;
;         }
;         unsigned hi[8], lo[8];
; #pragma unroll
;         for (int i = 0; i < 8; ++i) {
;           hi[i] = pack2(lf[2 * i], lf[2 * i + 1]);
;           lo[i] = pack2(lf[2 * i] - bflo(hi[i]), lf[2 * i + 1] - bfhi(hi[i]));
;         }
;         f32x16 aft;
; #pragma unroll
;         for (int i = 0; i < 16; ++i) aft[i] = 0.f;
;         aft = mfma32(Tm0, mk8(hi[0], hi[1], hi[2], hi[3]), aft);
;         aft = mfma32(Tm1, mk8(hi[4], hi[5], hi[6], hi[7]), aft);
;         aft = mfma32(Tm0, mk8(lo[0], lo[1], lo[2], lo[3]), aft);
;         aft = mfma32(Tm1, mk8(lo[4], lo[5], lo[6], lo[7]), aft);
;         float w[16];
; #pragma unroll
;         for (int i = 0; i < 16; ++i) w[i] = ex2(lsg[i] + aft[i] + carry);
;         tsum += __shfl_xor(tsum, 32);
;         carry += tsum;
;         bf16x8 pk0 = mk8(pack2(w[0], w[1]), pack2(w[2], w[3]), pack2(w[4], w[5]), pack2(w[6], w[7]));
;         bf16x8 pk1 = mk8(pack2(w[8], w[9]), pack2(w[10], w[11]), pack2(w[12], w[13]), pack2(w[14], w[15]));
;         O1a = mfma32(vf[0][0], pk0, O1a);
;         O1b = mfma32(vf[0][1], pk0, O1b);
;         O1a = mfma32(vf[1][0], pk1, O1a);
;         O1b = mfma32(vf[1][1], pk1, O1b);
	s_or_b64 s[0:1], s[2:3], s[0:1]
	v_cndmask_b32_e64 v157, v128, v35, s[0:1]
	v_cndmask_b32_e64 v41, 0, -v41, s[0:1]
	v_add_f32_e32 v35, 1.0, v36
	v_log_f32_e32 v35, v35
	v_max_f32_e32 v36, v42, v42
	v_max_f32_e32 v42, 0, v36
	v_min_f32_e32 v36, 0, v36
	v_add_f32_e32 v42, v42, v35
	v_sub_f32_e32 v35, v36, v35
	v_add_u32_e32 v36, 11, v135
	v_cmp_lt_i32_e64 s[0:1], 0, v36
	v_exp_f32_e64 v36, -|v43|
	s_or_b64 s[0:1], s[2:3], s[0:1]
	v_cndmask_b32_e64 v165, v128, v35, s[0:1]
	v_cndmask_b32_e64 v42, 0, -v42, s[0:1]
	v_add_f32_e32 v35, 1.0, v36
	v_log_f32_e32 v35, v35
	v_max_f32_e32 v36, v43, v43
	v_max_f32_e32 v43, 0, v36
	v_min_f32_e32 v36, 0, v36
	v_add_f32_e32 v43, v43, v35
	v_sub_f32_e32 v35, v36, v35
	v_add_u32_e32 v36, 10, v135
	v_cmp_lt_i32_e64 s[0:1], 0, v36
	v_exp_f32_e64 v36, -|v44|
	s_or_b64 s[0:1], s[2:3], s[0:1]
	v_cndmask_b32_e64 v174, v128, v35, s[0:1]
	v_cndmask_b32_e64 v167, 0, -v43, s[0:1]
	v_add_f32_e32 v35, 1.0, v36
	v_log_f32_e32 v35, v35
	v_max_f32_e32 v36, v44, v44
	v_max_f32_e32 v43, 0, v36
	v_min_f32_e32 v36, 0, v36
	v_add_f32_e32 v43, v43, v35
	v_sub_f32_e32 v35, v36, v35
	v_add_u32_e32 v36, 9, v135
	v_cmp_lt_i32_e64 s[0:1], 0, v36
	v_exp_f32_e64 v36, -|v45|
	s_or_b64 s[0:1], s[2:3], s[0:1]
	v_cndmask_b32_e64 v175, v128, v35, s[0:1]
	v_cndmask_b32_e64 v171, 0, -v43, s[0:1]
	v_add_f32_e32 v35, 1.0, v36
	v_log_f32_e32 v35, v35
	v_max_f32_e32 v36, v45, v45
	v_max_f32_e32 v43, 0, v36
	v_min_f32_e32 v36, 0, v36
	v_add_f32_e32 v43, v43, v35
	v_sub_f32_e32 v35, v36, v35
	v_add_u32_e32 v36, 8, v135
	v_cmp_lt_i32_e64 s[0:1], 0, v36
	v_exp_f32_e64 v36, -|v46|
	s_or_b64 s[0:1], s[2:3], s[0:1]
	v_cndmask_b32_e64 v176, v128, v35, s[0:1]
	v_cndmask_b32_e64 v172, 0, -v43, s[0:1]
	v_add_f32_e32 v35, 1.0, v36
	v_log_f32_e32 v35, v35
	v_max_f32_e32 v36, v46, v46
	v_max_f32_e32 v43, 0, v36
	v_min_f32_e32 v36, 0, v36
	v_add_f32_e32 v43, v43, v35
	v_sub_f32_e32 v35, v36, v35
	v_add_u32_e32 v36, 3, v135
	v_cmp_lt_i32_e64 s[0:1], 0, v36
	v_exp_f32_e64 v36, -|v47|
	s_or_b64 s[0:1], s[2:3], s[0:1]
	v_cndmask_b32_e64 v177, v128, v35, s[0:1]
	v_cndmask_b32_e64 v173, 0, -v43, s[0:1]
	v_add_f32_e32 v35, 1.0, v36
	v_log_f32_e32 v35, v35
	v_max_f32_e32 v36, v47, v47
	v_max_f32_e32 v43, 0, v36
	v_min_f32_e32 v36, 0, v36
	v_add_f32_e32 v43, v43, v35
	v_sub_f32_e32 v35, v36, v35
	v_add_u32_e32 v36, 2, v135
	v_cmp_lt_i32_e64 s[0:1], 0, v36
	v_exp_f32_e64 v36, -|v48|
	s_or_b64 s[0:1], s[2:3], s[0:1]
	v_cndmask_b32_e64 v179, v128, v35, s[0:1]
	v_add_f32_e32 v34, 0, v107
	v_add_f32_e32 v35, 1.0, v36
	v_log_f32_e32 v35, v35
	v_add_f32_e32 v34, v111, v34
	v_max_f32_e32 v36, v48, v48
	v_add_f32_e32 v34, v105, v34
	v_cndmask_b32_e64 v178, 0, -v43, s[0:1]
	v_max_f32_e32 v43, 0, v36
	v_min_f32_e32 v36, 0, v36
	v_add_f32_e32 v34, v37, v34
	v_add_f32_e32 v43, v43, v35
	v_sub_f32_e32 v35, v36, v35
	v_add_u32_e32 v36, 1, v135
	v_add_f32_e32 v34, v38, v34
	v_cmp_lt_i32_e64 s[0:1], 0, v36
	v_exp_f32_e64 v36, -|v49|
	v_add_f32_e32 v34, v39, v34
	v_add_f32_e32 v34, v40, v34
	v_add_f32_e32 v34, v41, v34
	s_or_b64 s[0:1], s[2:3], s[0:1]
	v_add_f32_e32 v34, v42, v34
	v_cndmask_b32_e64 v181, v128, v35, s[0:1]
	v_add_f32_e32 v35, 1.0, v36
	v_add_f32_e32 v34, v167, v34
	v_log_f32_e32 v35, v35
	v_add_f32_e32 v34, v171, v34
	v_add_f32_e32 v34, v172, v34
	v_max_f32_e32 v36, v49, v49
	v_add_f32_e32 v34, v173, v34
	v_cndmask_b32_e64 v180, 0, -v43, s[0:1]
	v_max_f32_e32 v43, 0, v36
	v_cmp_lt_i32_e64 s[0:1], 0, v135
	v_add_f32_e32 v34, v178, v34
	v_add_f32_e32 v43, v43, v35
	s_or_b64 s[0:1], s[2:3], s[0:1]
	v_add_f32_e32 v34, v180, v34
	v_min_f32_e32 v36, 0, v36
	v_cndmask_b32_e64 v182, 0, -v43, s[0:1]
	v_sub_f32_e32 v35, v36, v35
	v_add_f32_e32 v184, v182, v34
	v_cvt_pk_bf16_f32 v34, v107, v111
	v_cndmask_b32_e64 v183, v128, v35, s[0:1]
	v_lshlrev_b32_e32 v35, 16, v34
	v_and_b32_e32 v36, 0xffff0000, v34
	v_sub_f32_e32 v35, v107, v35
	v_sub_f32_e32 v36, v111, v36
	v_cvt_pk_bf16_f32 v152, v35, v36
	v_cvt_pk_bf16_f32 v35, v105, v37
	v_lshlrev_b32_e32 v36, 16, v35
	v_and_b32_e32 v43, 0xffff0000, v35
	v_sub_f32_e32 v36, v105, v36
	v_sub_f32_e32 v37, v37, v43
	v_cvt_pk_bf16_f32 v153, v36, v37
	v_cvt_pk_bf16_f32 v36, v38, v39
	v_lshlrev_b32_e32 v37, 16, v36
	v_sub_f32_e32 v37, v38, v37
	v_and_b32_e32 v38, 0xffff0000, v36
	v_sub_f32_e32 v38, v39, v38
	v_cvt_pk_bf16_f32 v154, v37, v38
	v_cvt_pk_bf16_f32 v37, v40, v41
	v_lshlrev_b32_e32 v38, 16, v37
	v_and_b32_e32 v39, 0xffff0000, v37
	v_sub_f32_e32 v38, v40, v38
	v_sub_f32_e32 v39, v41, v39
	v_cvt_pk_bf16_f32 v166, v42, v167
	v_cvt_pk_bf16_f32 v155, v38, v39
	v_lshlrev_b32_e32 v38, 16, v166
	v_sub_f32_e32 v105, v42, v38
	v_mfma_f32_32x32x16_bf16 v[34:49], v[66:69], v[34:37], 0
	v_and_b32_e32 v107, 0xffff0000, v166
	v_sub_f32_e32 v107, v167, v107
	v_cvt_pk_bf16_f32 v167, v171, v172
	v_cvt_pk_bf16_f32 v168, v173, v178
	v_cvt_pk_bf16_f32 v169, v180, v182
	v_cvt_pk_bf16_f32 v170, v105, v107
	v_lshlrev_b32_e32 v105, 16, v167
	v_mfma_f32_32x32x16_bf16 v[34:49], v[78:81], v[166:169], v[34:49]
	v_and_b32_e32 v107, 0xffff0000, v167
	v_sub_f32_e32 v105, v171, v105
	v_sub_f32_e32 v107, v172, v107
	v_cvt_pk_bf16_f32 v171, v105, v107
	v_lshlrev_b32_e32 v105, 16, v168
	v_and_b32_e32 v107, 0xffff0000, v168
	v_sub_f32_e32 v105, v173, v105
	v_mfma_f32_32x32x16_bf16 v[34:49], v[66:69], v[152:155], v[34:49]
	v_sub_f32_e32 v107, v178, v107
	v_cvt_pk_bf16_f32 v172, v105, v107
	v_lshlrev_b32_e32 v105, 16, v169
	v_and_b32_e32 v107, 0xffff0000, v169
	v_sub_f32_e32 v105, v180, v105
	v_sub_f32_e32 v107, v182, v107
	v_cvt_pk_bf16_f32 v173, v105, v107
	s_nop 1
	v_mfma_f32_32x32x16_bf16 v[34:49], v[78:81], v[170:173], v[34:49]
	s_nop 11
	v_add_f32_e32 v0, v0, v34
	v_add_f32_e32 v34, v113, v35
	v_add_f32_e32 v35, v115, v36
	v_add_f32_e32 v36, v109, v37
	v_add_f32_e32 v37, v117, v38
	v_add_f32_e32 v38, v151, v39
	v_add_f32_e32 v39, v156, v40
	v_add_f32_e32 v40, v157, v41
	v_add_f32_e32 v0, v138, v0
	v_add_f32_e32 v34, v138, v34
	v_add_f32_e32 v35, v138, v35
	v_add_f32_e32 v36, v138, v36
	v_add_f32_e32 v37, v138, v37
	v_add_f32_e32 v38, v138, v38
	v_add_f32_e32 v39, v138, v39
	v_add_f32_e32 v40, v138, v40
	v_exp_f32_e32 v0, v0
	v_exp_f32_e32 v34, v34
	v_exp_f32_e32 v35, v35
	v_exp_f32_e32 v36, v36
	v_exp_f32_e32 v37, v37
	v_exp_f32_e32 v38, v38
	v_exp_f32_e32 v39, v39
	v_exp_f32_e32 v40, v40
	v_cvt_pk_bf16_f32 v34, v0, v34
	v_cvt_pk_bf16_f32 v35, v35, v36
	v_cvt_pk_bf16_f32 v36, v37, v38
	v_cvt_pk_bf16_f32 v37, v39, v40
	v_add_f32_e32 v41, v165, v42
	v_add_f32_e32 v42, v174, v43
	v_mfma_f32_32x32x16_bf16 v[18:33], v[94:97], v[34:37], v[18:33]
	v_add_f32_e32 v43, v175, v44
	v_add_f32_e32 v44, v176, v45
	v_add_f32_e32 v45, v177, v46
	v_add_f32_e32 v38, v179, v47
	v_add_f32_e32 v39, v181, v48
	v_add_f32_e32 v41, v138, v41
	v_add_f32_e32 v42, v138, v42
	s_waitcnt lgkmcnt(2)
; DI f32x16 mfma32(bf16x8 a, bf16x8 b, f32x16 c) { return __builtin_amdgcn_mfma_f32_32x32x16_bf16(a, b, c, 0, 0, 0); }
; DI float ex2(float x) { return __builtin_amdgcn_exp2f(x); }
; template <int TYPE>
; DI void attn_item(const Params& p, int layer, int head, int qt, int dil, int res, int chunk, char* smem) {
;     ...
;         float w[16];
; #pragma unroll
;         for (int i = 0; i < 16; ++i) w[i] = ex2(lsg[i] + aft[i] + carry);
;         tsum += __shfl_xor(tsum, 32);
;         carry += tsum;
;         bf16x8 pk0 = mk8(pack2(w[0], w[1]), pack2(w[2], w[3]), pack2(w[4], w[5]), pack2(w[6], w[7]));
;         bf16x8 pk1 = mk8(pack2(w[8], w[9]), pack2(w[10], w[11]), pack2(w[12], w[13]), pack2(w[14], w[15]));
;         O1a = mfma32(vf[0][0], pk0, O1a);
;         O1b = mfma32(vf[0][1], pk0, O1b);
;         O1a = mfma32(vf[1][0], pk1, O1a);
;         O1b = mfma32(vf[1][1], pk1, O1b);
	v_mfma_f32_32x32x16_bf16 v[2:17], v[90:93], v[34:37], v[2:17]
	v_add_f32_e32 v34, v183, v49
	v_add_f32_e32 v43, v138, v43
	v_add_f32_e32 v44, v138, v44
	v_add_f32_e32 v45, v138, v45
	v_add_f32_e32 v38, v138, v38
	v_add_f32_e32 v39, v138, v39
	v_add_f32_e32 v34, v138, v34
	v_exp_f32_e32 v41, v41
	v_exp_f32_e32 v42, v42
	v_exp_f32_e32 v43, v43
	v_exp_f32_e32 v44, v44
	v_exp_f32_e32 v0, v45
	v_exp_f32_e32 v38, v38
	v_exp_f32_e32 v39, v39
	v_exp_f32_e32 v37, v34
	v_cvt_pk_bf16_f32 v34, v41, v42
	v_cvt_pk_bf16_f32 v35, v43, v44
	v_cvt_pk_bf16_f32 v36, v0, v38
	v_cvt_pk_bf16_f32 v37, v39, v37
	ds_bpermute_b32 v0, v159, v184
	s_waitcnt lgkmcnt(0)
	v_add_f32_e32 v0, v184, v0
	v_mfma_f32_32x32x16_bf16 v[18:33], v[86:89], v[34:37], v[18:33]
	v_add_f32_e32 v138, v138, v0
	v_mfma_f32_32x32x16_bf16 v[2:17], v[82:85], v[34:37], v[2:17]

; template <int TYPE>
; DI void attn_item(const Params& p, int layer, int head, int qt, int dil, int res, int chunk, char* smem) {
;     ...
;       const int Ks = Kb + 32 * sub;
;       bool need;
;       if (TYPE == 0) need = (Ks <= wq0 + 31) && (Ks + 31 >= wq0 - 128);
;       else if (TYPE == 1) need = (Ks <= wq0 + 31);
;       else need = (Ks < wq0 + 31) && (sflag[wid] == 0);
;       if (!need) continue;
;     ...
;       {
;         bf16x8 kf[4];
; #pragma unroll
;         for (int ks = 0; ks < 4; ++ks) kf[ks] = *(const bf16x8*)(sK + swz(32 * sub + ql, 2 * ks + h));
;         if (TYPE == 1) {
;           s1 = mfma32(kf[0], qf[0], s1);
;           s1 = mfma32(kf[1], qf[1], s1);
;           s2 = mfma32(kf[2], qf[2], s2);
;           s2 = mfma32(kf[3], qf[3], s2);
;         } else {
; #pragma unroll
;           for (int ks = 0; ks < 4; ++ks) s1 = mfma32(kf[ks], qf[ks], s1);
;         }
;       }
;       bf16x8 vf[2][2];
; #pragma unroll
;       for (int s = 0; s < 2; ++s)
; #pragma unroll
;         for (int dt = 0; dt < 2; ++dt) vf[s][dt] = *(const bf16x8*)(sV + swz(32 * dt + ql, 4 * sub + 2 * s + h));
;       if (TYPE == 0 || TYPE == 1) {
;         const bool masked = (TYPE == 0) ? true : (Ks + 31 > wq0);
;         bf16x8 pk0, pk1;
;         fx_step(s1, l1, db, masked, wlim, pk0, pk1);
;         O1a = mfma32(vf[0][0], pk0, O1a);
;         O1b = mfma32(vf[0][1], pk0, O1b);
;         O1a = mfma32(vf[1][0], pk1, O1a);
;         O1b = mfma32(vf[1][1], pk1, O1b);
;         if (TYPE == 1) {
;           fx_step(s2, l2, db, masked, wlim, pk0, pk1);
;           O2a = mfma32(vf[0][0], pk0, O2a);
;           O2b = mfma32(vf[0][1], pk0, O2b);
;           O2a = mfma32(vf[1][0], pk1, O2a);
;           O2b = mfma32(vf[1][1], pk1, O2b);
;         }
;       } else {
;         const bool masked = (Ks + 31 >= wq0);
;         float lf[16], lsg[16];
;         float tsum = 0.f;
; #pragma unroll
;         for (int i = 0; i < 16; ++i) {
;           const int ci = (i & 3) + 8 * (i >> 2);
;           const float z = s1[i];
;           const float t = lg2(1.f + ex2(-fabsf(z)));
;           float f = -(fmaxf(z, 0.f) + t);
;           float g = fminf(z, 0.f) - t;
;           if (masked) {
;             const bool ok = (db - ci) > 0;
;             f = ok ? f : 0.f;
;             g = ok ? g : -1e30f;
;           }
;           lf[i] = f;
;           lsg[i] = g;
;           tsum += f;
;         }
.LBB0_615:
	s_or_b64 exec, exec, s[54:55]
	v_add_u32_e32 v0, 0x3fc0, v99
	v_cmp_lt_i32_e64 s[0:1], v0, v133
	s_and_saveexec_b64 s[54:55], s[0:1]
	s_cbranch_execz .LBB0_619
	ds_read_b32 v0, v124
	s_waitcnt lgkmcnt(0)
	v_cmp_eq_u32_e64 s[0:1], 0, v0
	s_and_saveexec_b64 s[56:57], s[0:1]
	s_cbranch_execz .LBB0_618
	ds_read_b128 v[34:37], v147
	ds_read_b128 v[94:97], v147 offset:8192
	ds_read_b128 v[82:85], v148
	ds_read_b128 v[90:93], v147 offset:12288
	v_add_u32_e32 v0, 0x3fdf, v99
	v_add_u32_e32 v105, 59, v135
	s_waitcnt lgkmcnt(3)
	v_mfma_f32_32x32x16_bf16 v[34:49], v[34:37], v[50:53], 0
	v_add_u32_e32 v107, 58, v135
	v_cmp_lt_i32_e64 s[2:3], v0, v130
	v_cmp_lt_i32_e64 s[0:1], 0, v105
	v_cmp_lt_i32_e64 s[4:5], 0, v107
	v_add_u32_e32 v109, 57, v135
	v_cmp_lt_i32_e64 s[6:7], 0, v109
	s_or_b64 s[0:1], s[2:3], s[0:1]
	s_waitcnt lgkmcnt(1)
	v_mfma_f32_32x32x16_bf16 v[34:49], v[82:85], v[54:57], v[34:49]
	ds_read_b128 v[152:155], v149
	ds_read_b128 v[166:169], v150
	ds_read_b128 v[86:89], v148 offset:8192
	ds_read_b128 v[82:85], v148 offset:12288
	s_waitcnt lgkmcnt(3)
	v_mfma_f32_32x32x16_bf16 v[34:49], v[152:155], v[58:61], v[34:49]
	s_waitcnt lgkmcnt(2)
	v_mfma_f32_32x32x16_bf16 v[34:49], v[166:169], v[62:65], v[34:49]
	s_nop 11
	v_exp_f32_e64 v0, -|v34|
	v_exp_f32_e64 v105, -|v35|
	v_exp_f32_e64 v107, -|v36|
	v_max_f32_e32 v34, v34, v34
	v_add_f32_e32 v0, 1.0, v0
	v_add_f32_e32 v105, 1.0, v105
	v_log_f32_e32 v0, v0
	v_add_f32_e32 v107, 1.0, v107
	v_log_f32_e32 v105, v105
	v_log_f32_e32 v107, v107
	v_exp_f32_e64 v109, -|v37|
	v_max_f32_e32 v35, v35, v35
	v_max_f32_e32 v36, v36, v36
	v_max_f32_e32 v111, 0, v34
	v_min_f32_e32 v34, 0, v34
	v_max_f32_e32 v113, 0, v35
	v_min_f32_e32 v35, 0, v35
	v_max_f32_e32 v115, 0, v36
	v_min_f32_e32 v36, 0, v36
	v_add_f32_e32 v111, v111, v0
	v_sub_f32_e32 v0, v34, v0
	v_add_f32_e32 v34, v113, v105
	v_sub_f32_e32 v35, v35, v105
	v_add_f32_e32 v105, v115, v107
	v_sub_f32_e32 v36, v36, v107
	v_cndmask_b32_e64 v107, 0, -v111, s[0:1]
	v_cndmask_b32_e64 v0, v128, v0, s[0:1]
	s_or_b64 s[0:1], s[2:3], s[4:5]
	v_cndmask_b32_e64 v113, v128, v35, s[0:1]
	v_add_f32_e32 v35, 1.0, v109
	v_log_f32_e32 v35, v35
	v_cndmask_b32_e64 v111, 0, -v34, s[0:1]
	s_or_b64 s[0:1], s[2:3], s[6:7]
	v_cndmask_b32_e64 v115, v128, v36, s[0:1]
	v_max_f32_e32 v36, v37, v37
	v_max_f32_e32 v37, 0, v36
	v_min_f32_e32 v36, 0, v36
	v_add_f32_e32 v37, v37, v35
	v_sub_f32_e32 v35, v36, v35
	v_add_u32_e32 v36, 56, v135
	v_cndmask_b32_e64 v105, 0, -v105, s[0:1]
	v_cmp_lt_i32_e64 s[0:1], 0, v36
	v_exp_f32_e64 v36, -|v38|
	s_or_b64 s[0:1], s[2:3], s[0:1]
	v_cndmask_b32_e64 v109, v128, v35, s[0:1]
	v_cndmask_b32_e64 v37, 0, -v37, s[0:1]
	v_add_f32_e32 v35, 1.0, v36
	v_log_f32_e32 v35, v35
	v_max_f32_e32 v36, v38, v38
	v_max_f32_e32 v38, 0, v36
	v_min_f32_e32 v36, 0, v36
	v_add_f32_e32 v38, v38, v35
	v_sub_f32_e32 v35, v36, v35
	v_add_u32_e32 v36, 51, v135
	v_cmp_lt_i32_e64 s[0:1], 0, v36
	v_exp_f32_e64 v36, -|v39|
	s_or_b64 s[0:1], s[2:3], s[0:1]
	v_cndmask_b32_e64 v117, v128, v35, s[0:1]
	v_cndmask_b32_e64 v38, 0, -v38, s[0:1]
	v_add_f32_e32 v35, 1.0, v36
	v_log_f32_e32 v35, v35
	v_max_f32_e32 v36, v39, v39
	v_max_f32_e32 v39, 0, v36
	v_min_f32_e32 v36, 0, v36
	v_add_f32_e32 v39, v39, v35
	v_sub_f32_e32 v35, v36, v35
	v_add_u32_e32 v36, 50, v135
	v_cmp_lt_i32_e64 s[0:1], 0, v36
	v_exp_f32_e64 v36, -|v40|
	s_or_b64 s[0:1], s[2:3], s[0:1]
	v_cndmask_b32_e64 v151, v128, v35, s[0:1]
	v_cndmask_b32_e64 v39, 0, -v39, s[0:1]
	v_add_f32_e32 v35, 1.0, v36
	v_log_f32_e32 v35, v35
	v_max_f32_e32 v36, v40, v40
	v_max_f32_e32 v40, 0, v36
	v_min_f32_e32 v36, 0, v36
	v_add_f32_e32 v40, v40, v35
	v_sub_f32_e32 v35, v36, v35
	v_add_u32_e32 v36, 49, v135
	v_cmp_lt_i32_e64 s[0:1], 0, v36
	v_exp_f32_e64 v36, -|v41|
	s_or_b64 s[0:1], s[2:3], s[0:1]
	v_cndmask_b32_e64 v156, v128, v35, s[0:1]
	v_cndmask_b32_e64 v40, 0, -v40, s[0:1]
	v_add_f32_e32 v35, 1.0, v36
	v_log_f32_e32 v35, v35
	v_max_f32_e32 v36, v41, v41
	v_max_f32_e32 v41, 0, v36
	v_min_f32_e32 v36, 0, v36
	v_add_f32_e32 v41, v41, v35
	v_sub_f32_e32 v35, v36, v35
	v_add_u32_e32 v36, 48, v135
	v_cmp_lt_i32_e64 s[0:1], 0, v36
	v_exp_f32_e64 v36, -|v42|
	s_or_b64 s[0:1], s[2:3], s[0:1]
	v_cndmask_b32_e64 v157, v128, v35, s[0:1]
	v_cndmask_b32_e64 v41, 0, -v41, s[0:1]
	v_add_f32_e32 v35, 1.0, v36
	v_log_f32_e32 v35, v35
	v_max_f32_e32 v36, v42, v42
	v_max_f32_e32 v42, 0, v36
	v_min_f32_e32 v36, 0, v36
	v_add_f32_e32 v42, v42, v35
	v_sub_f32_e32 v35, v36, v35
	v_add_u32_e32 v36, 43, v135
	v_cmp_lt_i32_e64 s[0:1], 0, v36
	v_exp_f32_e64 v36, -|v43|
	s_or_b64 s[0:1], s[2:3], s[0:1]
	v_cndmask_b32_e64 v165, v128, v35, s[0:1]
	v_cndmask_b32_e64 v42, 0, -v42, s[0:1]
	v_add_f32_e32 v35, 1.0, v36
	v_log_f32_e32 v35, v35
	v_max_f32_e32 v36, v43, v43
	v_max_f32_e32 v43, 0, v36
	v_min_f32_e32 v36, 0, v36
	v_add_f32_e32 v43, v43, v35
	v_sub_f32_e32 v35, v36, v35
	v_add_u32_e32 v36, 42, v135
	v_cmp_lt_i32_e64 s[0:1], 0, v36
	v_exp_f32_e64 v36, -|v44|
	s_or_b64 s[0:1], s[2:3], s[0:1]
	v_cndmask_b32_e64 v174, v128, v35, s[0:1]
	v_cndmask_b32_e64 v167, 0, -v43, s[0:1]
	v_add_f32_e32 v35, 1.0, v36
	v_log_f32_e32 v35, v35
	v_max_f32_e32 v36, v44, v44
	v_max_f32_e32 v43, 0, v36
	v_min_f32_e32 v36, 0, v36
	v_add_f32_e32 v43, v43, v35
	v_sub_f32_e32 v35, v36, v35
	v_add_u32_e32 v36, 41, v135
	v_cmp_lt_i32_e64 s[0:1], 0, v36
	v_exp_f32_e64 v36, -|v45|
	s_or_b64 s[0:1], s[2:3], s[0:1]
	v_cndmask_b32_e64 v175, v128, v35, s[0:1]
	v_cndmask_b32_e64 v171, 0, -v43, s[0:1]
	v_add_f32_e32 v35, 1.0, v36
	v_log_f32_e32 v35, v35
	v_max_f32_e32 v36, v45, v45
	v_max_f32_e32 v43, 0, v36
	v_min_f32_e32 v36, 0, v36
	v_add_f32_e32 v43, v43, v35
; DI float bflo(unsigned u) { return __uint_as_float(u << 16); }
; DI float bfhi(unsigned u) { return __uint_as_float(u & 0xffff0000u); }
; DI f32x16 mfma32(bf16x8 a, bf16x8 b, f32x16 c) { return __builtin_amdgcn_mfma_f32_32x32x16_bf16(a, b, c, 0, 0, 0); }
; DI float ex2(float x) { return __builtin_amdgcn_exp2f(x); }
; DI float lg2(float x) { return __builtin_amdgcn_logf(x); }
; template <int TYPE>
; DI void attn_item(const Params& p, int layer, int head, int qt, int dil, int res, int chunk, char* smem) {
;     ...
;         for (int i = 0; i < 16; ++i) {
;           const int ci = (i & 3) + 8 * (i >> 2);
;           const float z = s1[i];
;           const float t = lg2(1.f + ex2(-fabsf(z)));
;           float f = -(fmaxf(z, 0.f) + t);
;           float g = fminf(z, 0.f) - t;
;           if (masked) {
;             const bool ok = (db - ci) > 0;
;             f = ok ? f : 0.f;
;             g = ok ? g : -1e30f;
;           }
;           lf[i] = f;
;           lsg[i] = g;
;           tsum += f;
;         }
;         unsigned hi[8], lo[8];
; #pragma unroll
;         for (int i = 0; i < 8; ++i) {
;           hi[i] = pack2(lf[2 * i], lf[2 * i + 1]);
;           lo[i] = pack2(lf[2 * i] - bflo(hi[i]), lf[2 * i + 1] - bfhi(hi[i]));
;         }
;         f32x16 aft;
; #pragma unroll
;         for (int i = 0; i < 16; ++i) aft[i] = 0.f;
;         aft = mfma32(Tm0, mk8(hi[0], hi[1], hi[2], hi[3]), aft);
;         aft = mfma32(Tm1, mk8(hi[4], hi[5], hi[6], hi[7]), aft);
;         aft = mfma32(Tm0, mk8(lo[0], lo[1], lo[2], lo[3]), aft);
;         aft = mfma32(Tm1, mk8(lo[4], lo[5], lo[6], lo[7]), aft);
;         float w[16];
; #pragma unroll
;         for (int i = 0; i < 16; ++i) w[i] = ex2(lsg[i] + aft[i] + carry);
;         tsum += __shfl_xor(tsum, 32);
;         carry += tsum;
;         bf16x8 pk0 = mk8(pack2(w[0], w[1]), pack2(w[2], w[3]), pack2(w[4], w[5]), pack2(w[6], w[7]));
;         bf16x8 pk1 = mk8(pack2(w[8], w[9]), pack2(w[10], w[11]), pack2(w[12], w[13]), pack2(w[14], w[15]));
;         O1a = mfma32(vf[0][0], pk0, O1a);
;         O1b = mfma32(vf[0][1], pk0, O1b);
;         O1a = mfma32(vf[1][0], pk1, O1a);
;         O1b = mfma32(vf[1][1], pk1, O1b);
	v_sub_f32_e32 v35, v36, v35
	v_add_u32_e32 v36, 40, v135
	v_cmp_lt_i32_e64 s[0:1], 0, v36
	v_exp_f32_e64 v36, -|v46|
	s_or_b64 s[0:1], s[2:3], s[0:1]
	v_cndmask_b32_e64 v176, v128, v35, s[0:1]
	v_cndmask_b32_e64 v172, 0, -v43, s[0:1]
	v_add_f32_e32 v35, 1.0, v36
	v_log_f32_e32 v35, v35
	v_max_f32_e32 v36, v46, v46
	v_max_f32_e32 v43, 0, v36
	v_min_f32_e32 v36, 0, v36
	v_add_f32_e32 v43, v43, v35
	v_sub_f32_e32 v35, v36, v35
	v_add_u32_e32 v36, 35, v135
	v_cmp_lt_i32_e64 s[0:1], 0, v36
	v_exp_f32_e64 v36, -|v47|
	s_or_b64 s[0:1], s[2:3], s[0:1]
	v_cndmask_b32_e64 v177, v128, v35, s[0:1]
	v_cndmask_b32_e64 v173, 0, -v43, s[0:1]
	v_add_f32_e32 v35, 1.0, v36
	v_log_f32_e32 v35, v35
	v_max_f32_e32 v36, v47, v47
	v_max_f32_e32 v43, 0, v36
	v_min_f32_e32 v36, 0, v36
	v_add_f32_e32 v43, v43, v35
	v_sub_f32_e32 v35, v36, v35
	v_add_u32_e32 v36, 34, v135
	v_cmp_lt_i32_e64 s[0:1], 0, v36
	v_exp_f32_e64 v36, -|v48|
	s_or_b64 s[0:1], s[2:3], s[0:1]
	v_cndmask_b32_e64 v179, v128, v35, s[0:1]
	v_add_f32_e32 v34, 0, v107
	v_add_f32_e32 v35, 1.0, v36
	v_log_f32_e32 v35, v35
	v_max_f32_e32 v36, v48, v48
	v_cndmask_b32_e64 v178, 0, -v43, s[0:1]
	v_max_f32_e32 v43, 0, v36
	v_min_f32_e32 v36, 0, v36
	v_add_f32_e32 v34, v111, v34
	v_add_f32_e32 v43, v43, v35
	v_sub_f32_e32 v35, v36, v35
	v_add_u32_e32 v36, 33, v135
	v_add_f32_e32 v34, v105, v34
	v_cmp_lt_i32_e64 s[0:1], 0, v36
	v_exp_f32_e64 v36, -|v49|
	v_add_f32_e32 v34, v37, v34
	v_add_f32_e32 v34, v38, v34
	v_add_f32_e32 v34, v39, v34
	s_or_b64 s[0:1], s[2:3], s[0:1]
	v_add_f32_e32 v34, v40, v34
	v_cndmask_b32_e64 v181, v128, v35, s[0:1]
	v_add_f32_e32 v35, 1.0, v36
	v_add_f32_e32 v34, v41, v34
	v_log_f32_e32 v35, v35
	v_add_f32_e32 v34, v42, v34
	v_add_f32_e32 v34, v167, v34
	v_max_f32_e32 v36, v49, v49
	v_add_f32_e32 v34, v171, v34
	v_cndmask_b32_e64 v180, 0, -v43, s[0:1]
	v_max_f32_e32 v43, 0, v36
	v_min_f32_e32 v36, 0, v36
	v_add_f32_e32 v34, v172, v34
	v_add_f32_e32 v43, v43, v35
	v_sub_f32_e32 v35, v36, v35
	v_add_u32_e32 v36, 32, v135
	v_add_f32_e32 v34, v173, v34
	v_cmp_lt_i32_e64 s[0:1], 0, v36
	v_add_f32_e32 v34, v178, v34
	s_or_b64 s[0:1], s[2:3], s[0:1]
	v_add_f32_e32 v34, v180, v34
	v_cndmask_b32_e64 v182, 0, -v43, s[0:1]
	v_add_f32_e32 v184, v182, v34
	v_cvt_pk_bf16_f32 v34, v107, v111
	v_cndmask_b32_e64 v183, v128, v35, s[0:1]
	v_lshlrev_b32_e32 v35, 16, v34
	v_and_b32_e32 v36, 0xffff0000, v34
	v_sub_f32_e32 v35, v107, v35
	v_sub_f32_e32 v36, v111, v36
	v_cvt_pk_bf16_f32 v152, v35, v36
	v_cvt_pk_bf16_f32 v35, v105, v37
	v_lshlrev_b32_e32 v36, 16, v35
	v_and_b32_e32 v43, 0xffff0000, v35
	v_sub_f32_e32 v36, v105, v36
	v_sub_f32_e32 v37, v37, v43
	v_cvt_pk_bf16_f32 v153, v36, v37
	v_cvt_pk_bf16_f32 v36, v38, v39
	v_lshlrev_b32_e32 v37, 16, v36
	v_sub_f32_e32 v37, v38, v37
	v_and_b32_e32 v38, 0xffff0000, v36
	v_sub_f32_e32 v38, v39, v38
	v_cvt_pk_bf16_f32 v154, v37, v38
	v_cvt_pk_bf16_f32 v37, v40, v41
	v_lshlrev_b32_e32 v38, 16, v37
	v_and_b32_e32 v39, 0xffff0000, v37
	v_sub_f32_e32 v38, v40, v38
	v_sub_f32_e32 v39, v41, v39
	v_cvt_pk_bf16_f32 v166, v42, v167
	v_cvt_pk_bf16_f32 v155, v38, v39
	v_lshlrev_b32_e32 v38, 16, v166
	v_sub_f32_e32 v105, v42, v38
	v_mfma_f32_32x32x16_bf16 v[34:49], v[66:69], v[34:37], 0
	v_and_b32_e32 v107, 0xffff0000, v166
	v_sub_f32_e32 v107, v167, v107
	v_cvt_pk_bf16_f32 v167, v171, v172
	v_cvt_pk_bf16_f32 v168, v173, v178
	v_cvt_pk_bf16_f32 v169, v180, v182
	v_cvt_pk_bf16_f32 v170, v105, v107
	v_lshlrev_b32_e32 v105, 16, v167
	v_mfma_f32_32x32x16_bf16 v[34:49], v[78:81], v[166:169], v[34:49]
	v_and_b32_e32 v107, 0xffff0000, v167
	v_sub_f32_e32 v105, v171, v105
	v_sub_f32_e32 v107, v172, v107
	v_cvt_pk_bf16_f32 v171, v105, v107
	v_lshlrev_b32_e32 v105, 16, v168
	v_and_b32_e32 v107, 0xffff0000, v168
	v_sub_f32_e32 v105, v173, v105
	v_mfma_f32_32x32x16_bf16 v[34:49], v[66:69], v[152:155], v[34:49]
	v_sub_f32_e32 v107, v178, v107
	v_cvt_pk_bf16_f32 v172, v105, v107
	v_lshlrev_b32_e32 v105, 16, v169
	v_and_b32_e32 v107, 0xffff0000, v169
	v_sub_f32_e32 v105, v180, v105
	v_sub_f32_e32 v107, v182, v107
	v_cvt_pk_bf16_f32 v173, v105, v107
	s_nop 1
	v_mfma_f32_32x32x16_bf16 v[34:49], v[78:81], v[170:173], v[34:49]
	s_nop 11
	v_add_f32_e32 v0, v0, v34
	v_add_f32_e32 v34, v113, v35
	v_add_f32_e32 v35, v115, v36
	v_add_f32_e32 v36, v109, v37
	v_add_f32_e32 v37, v117, v38
	v_add_f32_e32 v38, v151, v39
	v_add_f32_e32 v39, v156, v40
	v_add_f32_e32 v40, v157, v41
	v_add_f32_e32 v0, v138, v0
	v_add_f32_e32 v34, v138, v34
	v_add_f32_e32 v35, v138, v35
	v_add_f32_e32 v36, v138, v36
	v_add_f32_e32 v37, v138, v37
	v_add_f32_e32 v38, v138, v38
	v_add_f32_e32 v39, v138, v39
	v_add_f32_e32 v40, v138, v40
	v_exp_f32_e32 v0, v0
	v_exp_f32_e32 v34, v34
	v_exp_f32_e32 v35, v35
	v_exp_f32_e32 v36, v36
	v_exp_f32_e32 v37, v37
	v_exp_f32_e32 v38, v38
	v_exp_f32_e32 v39, v39
	v_exp_f32_e32 v40, v40
	v_cvt_pk_bf16_f32 v34, v0, v34
	v_cvt_pk_bf16_f32 v35, v35, v36
	v_cvt_pk_bf16_f32 v36, v37, v38
	v_cvt_pk_bf16_f32 v37, v39, v40
	v_add_f32_e32 v41, v165, v42
	v_add_f32_e32 v42, v174, v43
	v_mfma_f32_32x32x16_bf16 v[18:33], v[94:97], v[34:37], v[18:33]
	v_add_f32_e32 v43, v175, v44
	v_add_f32_e32 v44, v176, v45
	v_add_f32_e32 v45, v177, v46
	v_add_f32_e32 v38, v179, v47
	v_add_f32_e32 v39, v181, v48
	v_add_f32_e32 v41, v138, v41
	v_add_f32_e32 v42, v138, v42
	v_mfma_f32_32x32x16_bf16 v[2:17], v[90:93], v[34:37], v[2:17]
	v_add_f32_e32 v34, v183, v49
	v_add_f32_e32 v43, v138, v43
	v_add_f32_e32 v44, v138, v44
	v_add_f32_e32 v45, v138, v45
	v_add_f32_e32 v38, v138, v38
	v_add_f32_e32 v39, v138, v39
	v_add_f32_e32 v34, v138, v34
	v_exp_f32_e32 v41, v41
	v_exp_f32_e32 v42, v42
	v_exp_f32_e32 v43, v43
	v_exp_f32_e32 v44, v44
	v_exp_f32_e32 v0, v45
	v_exp_f32_e32 v38, v38
	v_exp_f32_e32 v39, v39
	v_exp_f32_e32 v37, v34
	v_cvt_pk_bf16_f32 v34, v41, v42
	v_cvt_pk_bf16_f32 v35, v43, v44
	v_cvt_pk_bf16_f32 v36, v0, v38
	v_cvt_pk_bf16_f32 v37, v39, v37
	ds_bpermute_b32 v0, v159, v184
	s_waitcnt lgkmcnt(0)
	v_add_f32_e32 v0, v184, v0
	v_mfma_f32_32x32x16_bf16 v[18:33], v[86:89], v[34:37], v[18:33]
	v_add_f32_e32 v138, v138, v0
	v_mfma_f32_32x32x16_bf16 v[2:17], v[82:85], v[34:37], v[2:17]
